# GEMM k-loops: first 2 LDS-DMA pieces issued right after the barrier, ahead of the fragment ds_reads
# speedup vs baseline: 1.0068x; 1.0068x over previous
.Lg0_top:
	s_waitcnt lgkmcnt(0)
	s_waitcnt vmcnt(0)
	s_barrier
	s_xor_b32 s87, s87, 0x10000
	s_mov_b32 m0, s87
	s_add_u32 s88, s60, s16
	s_addc_u32 s89, s61, s17
	global_load_lds_dwordx4 v144, s[88:89]
	s_add_u32 m0, s87, 0x2000
	s_add_u32 s88, s60, s18
	s_addc_u32 s89, s61, s19
	global_load_lds_dwordx4 v144, s[88:89]
	ds_read_b128 v[156:159], v143
	ds_read_b128 v[160:163], v143 offset:2048
	ds_read_b128 v[164:167], v143 offset:4096
	ds_read_b128 v[168:171], v143 offset:6144
	ds_read_b128 v[190:193], v180 offset:32768
	ds_read_b128 v[194:197], v180 offset:34816
	ds_read_b128 v[198:201], v180 offset:36864
	ds_read_b128 v[202:205], v180 offset:38912
	v_mfma_f32_16x16x32_bf16 v[60:63], v[172:175], v[206:209], v[60:63]
	v_mfma_f32_16x16x32_bf16 v[52:55], v[172:175], v[210:213], v[52:55]
	s_add_u32 m0, s87, 0x4000
	s_add_u32 s88, s60, s22
	s_addc_u32 s89, s61, s23
	global_load_lds_dwordx4 v144, s[88:89]
	v_mfma_f32_16x16x32_bf16 v[56:59], v[172:175], v[214:217], v[56:59]
	v_mfma_f32_16x16x32_bf16 v[48:51], v[172:175], v[218:221], v[48:51]
	s_add_u32 m0, s87, 0x6000
	s_add_u32 s88, s60, s40
	s_addc_u32 s89, s61, s41
	global_load_lds_dwordx4 v144, s[88:89]
	v_mfma_f32_16x16x32_bf16 v[44:47], v[176:179], v[206:209], v[44:47]
	v_mfma_f32_16x16x32_bf16 v[36:39], v[176:179], v[210:213], v[36:39]
	s_add_u32 m0, s87, 0x8000
	s_add_u32 s88, s60, s42
	s_addc_u32 s89, s61, s43
	global_load_lds_dwordx4 v145, s[88:89]
	v_mfma_f32_16x16x32_bf16 v[40:43], v[176:179], v[214:217], v[40:43]
	v_mfma_f32_16x16x32_bf16 v[32:35], v[176:179], v[218:221], v[32:35]
	s_add_u32 m0, s87, 0xa000
	s_add_u32 s88, s60, s52
	s_addc_u32 s89, s61, s53
	global_load_lds_dwordx4 v145, s[88:89]
	v_mfma_f32_16x16x32_bf16 v[28:31], v[182:185], v[206:209], v[28:31]
	v_mfma_f32_16x16x32_bf16 v[16:19], v[182:185], v[210:213], v[16:19]
	s_add_u32 m0, s87, 0xc000
	s_add_u32 s88, s60, s54
	s_addc_u32 s89, s61, s55
	global_load_lds_dwordx4 v145, s[88:89]
	v_mfma_f32_16x16x32_bf16 v[24:27], v[182:185], v[214:217], v[24:27]
	v_mfma_f32_16x16x32_bf16 v[12:15], v[182:185], v[218:221], v[12:15]
	s_add_u32 m0, s87, 0xe000
	s_add_u32 s88, s60, s56
	s_addc_u32 s89, s61, s57
	global_load_lds_dwordx4 v145, s[88:89]
	v_mfma_f32_16x16x32_bf16 v[4:7], v[186:189], v[206:209], v[4:7]
	v_mfma_f32_16x16x32_bf16 v[0:3], v[186:189], v[210:213], v[0:3]
	v_mfma_f32_16x16x32_bf16 v[20:23], v[186:189], v[214:217], v[20:23]
	v_mfma_f32_16x16x32_bf16 v[8:11], v[186:189], v[218:221], v[8:11]
.Lg0_entry:
	ds_read_b128 v[172:175], v143 offset:8192
	ds_read_b128 v[176:179], v143 offset:10240
	ds_read_b128 v[182:185], v143 offset:12288
	ds_read_b128 v[186:189], v143 offset:14336
	s_waitcnt lgkmcnt(4)
	v_mfma_f32_16x16x32_bf16 v[124:127], v[156:159], v[190:193], v[124:127]
	v_mfma_f32_16x16x32_bf16 v[116:119], v[156:159], v[194:197], v[116:119]
	v_mfma_f32_16x16x32_bf16 v[120:123], v[156:159], v[198:201], v[120:123]
	v_mfma_f32_16x16x32_bf16 v[112:115], v[156:159], v[202:205], v[112:115]
	v_mfma_f32_16x16x32_bf16 v[108:111], v[160:163], v[190:193], v[108:111]
	v_mfma_f32_16x16x32_bf16 v[100:103], v[160:163], v[194:197], v[100:103]
	v_mfma_f32_16x16x32_bf16 v[104:107], v[160:163], v[198:201], v[104:107]
	v_mfma_f32_16x16x32_bf16 v[96:99], v[160:163], v[202:205], v[96:99]
	v_mfma_f32_16x16x32_bf16 v[92:95], v[164:167], v[190:193], v[92:95]
	v_mfma_f32_16x16x32_bf16 v[84:87], v[164:167], v[194:197], v[84:87]
	v_mfma_f32_16x16x32_bf16 v[88:91], v[164:167], v[198:201], v[88:91]
	v_mfma_f32_16x16x32_bf16 v[80:83], v[164:167], v[202:205], v[80:83]
	v_mfma_f32_16x16x32_bf16 v[76:79], v[168:171], v[190:193], v[76:79]
	v_mfma_f32_16x16x32_bf16 v[68:71], v[168:171], v[194:197], v[68:71]
	v_mfma_f32_16x16x32_bf16 v[72:75], v[168:171], v[198:201], v[72:75]
	v_mfma_f32_16x16x32_bf16 v[64:67], v[168:171], v[202:205], v[64:67]
	ds_read_b128 v[156:159], v155
	ds_read_b128 v[160:163], v155 offset:2048
	ds_read_b128 v[164:167], v155 offset:4096
	ds_read_b128 v[168:171], v155 offset:6144
	ds_read_b128 v[206:209], v222 offset:32768
	ds_read_b128 v[210:213], v222 offset:34816
	ds_read_b128 v[214:217], v222 offset:36864
	ds_read_b128 v[218:221], v222 offset:38912
	s_waitcnt lgkmcnt(8)
	v_mfma_f32_16x16x32_bf16 v[60:63], v[172:175], v[190:193], v[60:63]
	v_mfma_f32_16x16x32_bf16 v[52:55], v[172:175], v[194:197], v[52:55]
	v_mfma_f32_16x16x32_bf16 v[56:59], v[172:175], v[198:201], v[56:59]
	v_mfma_f32_16x16x32_bf16 v[48:51], v[172:175], v[202:205], v[48:51]
	v_mfma_f32_16x16x32_bf16 v[44:47], v[176:179], v[190:193], v[44:47]
	v_mfma_f32_16x16x32_bf16 v[36:39], v[176:179], v[194:197], v[36:39]
	v_mfma_f32_16x16x32_bf16 v[40:43], v[176:179], v[198:201], v[40:43]
	v_mfma_f32_16x16x32_bf16 v[32:35], v[176:179], v[202:205], v[32:35]
	v_mfma_f32_16x16x32_bf16 v[28:31], v[182:185], v[190:193], v[28:31]
	v_mfma_f32_16x16x32_bf16 v[16:19], v[182:185], v[194:197], v[16:19]
	v_mfma_f32_16x16x32_bf16 v[24:27], v[182:185], v[198:201], v[24:27]
	v_mfma_f32_16x16x32_bf16 v[12:15], v[182:185], v[202:205], v[12:15]
	v_mfma_f32_16x16x32_bf16 v[4:7], v[186:189], v[190:193], v[4:7]
	v_mfma_f32_16x16x32_bf16 v[0:3], v[186:189], v[194:197], v[0:3]
	v_mfma_f32_16x16x32_bf16 v[20:23], v[186:189], v[198:201], v[20:23]
	v_mfma_f32_16x16x32_bf16 v[8:11], v[186:189], v[202:205], v[8:11]
	ds_read_b128 v[172:175], v155 offset:8192
	ds_read_b128 v[176:179], v155 offset:10240
	ds_read_b128 v[182:185], v155 offset:12288
	ds_read_b128 v[186:189], v155 offset:14336
	s_waitcnt lgkmcnt(4)
	v_mfma_f32_16x16x32_bf16 v[124:127], v[156:159], v[206:209], v[124:127]
	v_mfma_f32_16x16x32_bf16 v[116:119], v[156:159], v[210:213], v[116:119]
	v_mfma_f32_16x16x32_bf16 v[120:123], v[156:159], v[214:217], v[120:123]
	v_mfma_f32_16x16x32_bf16 v[112:115], v[156:159], v[218:221], v[112:115]
	v_mfma_f32_16x16x32_bf16 v[108:111], v[160:163], v[206:209], v[108:111]
	v_mfma_f32_16x16x32_bf16 v[100:103], v[160:163], v[210:213], v[100:103]
	v_mfma_f32_16x16x32_bf16 v[104:107], v[160:163], v[214:217], v[104:107]
	v_mfma_f32_16x16x32_bf16 v[96:99], v[160:163], v[218:221], v[96:99]
	v_mfma_f32_16x16x32_bf16 v[92:95], v[164:167], v[206:209], v[92:95]
	v_mfma_f32_16x16x32_bf16 v[84:87], v[164:167], v[210:213], v[84:87]
	v_mfma_f32_16x16x32_bf16 v[88:91], v[164:167], v[214:217], v[88:91]
	v_mfma_f32_16x16x32_bf16 v[80:83], v[164:167], v[218:221], v[80:83]
	v_mfma_f32_16x16x32_bf16 v[76:79], v[168:171], v[206:209], v[76:79]
	v_mfma_f32_16x16x32_bf16 v[68:71], v[168:171], v[210:213], v[68:71]
	v_mfma_f32_16x16x32_bf16 v[72:75], v[168:171], v[214:217], v[72:75]
	v_mfma_f32_16x16x32_bf16 v[64:67], v[168:171], v[218:221], v[64:67]
	s_add_u32 s60, s60, 0x80
	s_addc_u32 s61, s61, 0
	s_add_i32 s59, s59, 1
	s_cmp_lt_u32 s59, 15
	s_cbranch_scc0 .Lg0_last
	s_waitcnt lgkmcnt(0)
	s_waitcnt vmcnt(0)
	s_barrier
	s_xor_b32 s87, s87, 0x10000
	s_mov_b32 m0, s87
	s_add_u32 s88, s60, s16
	s_addc_u32 s89, s61, s17
	global_load_lds_dwordx4 v144, s[88:89]
	s_add_u32 m0, s87, 0x2000
	s_add_u32 s88, s60, s18
	s_addc_u32 s89, s61, s19
	global_load_lds_dwordx4 v144, s[88:89]
	ds_read_b128 v[156:159], v223
	ds_read_b128 v[160:163], v223 offset:2048
	ds_read_b128 v[164:167], v223 offset:4096
	ds_read_b128 v[168:171], v223 offset:6144
	ds_read_b128 v[190:193], v225 offset:32768
	ds_read_b128 v[194:197], v225 offset:34816
	ds_read_b128 v[198:201], v225 offset:36864
	ds_read_b128 v[202:205], v225 offset:38912
	v_mfma_f32_16x16x32_bf16 v[60:63], v[172:175], v[206:209], v[60:63]
	v_mfma_f32_16x16x32_bf16 v[52:55], v[172:175], v[210:213], v[52:55]
	s_add_u32 m0, s87, 0x4000
	s_add_u32 s88, s60, s22
	s_addc_u32 s89, s61, s23
	global_load_lds_dwordx4 v144, s[88:89]
	v_mfma_f32_16x16x32_bf16 v[56:59], v[172:175], v[214:217], v[56:59]
	v_mfma_f32_16x16x32_bf16 v[48:51], v[172:175], v[218:221], v[48:51]
	s_add_u32 m0, s87, 0x6000
	s_add_u32 s88, s60, s40
	s_addc_u32 s89, s61, s41
	global_load_lds_dwordx4 v144, s[88:89]
	v_mfma_f32_16x16x32_bf16 v[44:47], v[176:179], v[206:209], v[44:47]
	v_mfma_f32_16x16x32_bf16 v[36:39], v[176:179], v[210:213], v[36:39]
	s_add_u32 m0, s87, 0x8000
	s_add_u32 s88, s60, s42
	s_addc_u32 s89, s61, s43
	global_load_lds_dwordx4 v145, s[88:89]
	v_mfma_f32_16x16x32_bf16 v[40:43], v[176:179], v[214:217], v[40:43]
	v_mfma_f32_16x16x32_bf16 v[32:35], v[176:179], v[218:221], v[32:35]
	s_add_u32 m0, s87, 0xa000
	s_add_u32 s88, s60, s52
	s_addc_u32 s89, s61, s53
	global_load_lds_dwordx4 v145, s[88:89]
	v_mfma_f32_16x16x32_bf16 v[28:31], v[182:185], v[206:209], v[28:31]
	v_mfma_f32_16x16x32_bf16 v[16:19], v[182:185], v[210:213], v[16:19]
	s_add_u32 m0, s87, 0xc000
	s_add_u32 s88, s60, s54
	s_addc_u32 s89, s61, s55
	global_load_lds_dwordx4 v145, s[88:89]
	v_mfma_f32_16x16x32_bf16 v[24:27], v[182:185], v[214:217], v[24:27]
	v_mfma_f32_16x16x32_bf16 v[12:15], v[182:185], v[218:221], v[12:15]
	s_add_u32 m0, s87, 0xe000
	s_add_u32 s88, s60, s56
	s_addc_u32 s89, s61, s57
	global_load_lds_dwordx4 v145, s[88:89]
	v_mfma_f32_16x16x32_bf16 v[4:7], v[186:189], v[206:209], v[4:7]
	v_mfma_f32_16x16x32_bf16 v[0:3], v[186:189], v[210:213], v[0:3]
	v_mfma_f32_16x16x32_bf16 v[20:23], v[186:189], v[214:217], v[20:23]
	v_mfma_f32_16x16x32_bf16 v[8:11], v[186:189], v[218:221], v[8:11]
	ds_read_b128 v[172:175], v223 offset:8192
	ds_read_b128 v[176:179], v223 offset:10240
	ds_read_b128 v[182:185], v223 offset:12288
	ds_read_b128 v[186:189], v223 offset:14336
	s_waitcnt lgkmcnt(4)
	v_mfma_f32_16x16x32_bf16 v[124:127], v[156:159], v[190:193], v[124:127]
	v_mfma_f32_16x16x32_bf16 v[116:119], v[156:159], v[194:197], v[116:119]
	v_mfma_f32_16x16x32_bf16 v[120:123], v[156:159], v[198:201], v[120:123]
	v_mfma_f32_16x16x32_bf16 v[112:115], v[156:159], v[202:205], v[112:115]
	v_mfma_f32_16x16x32_bf16 v[108:111], v[160:163], v[190:193], v[108:111]
	v_mfma_f32_16x16x32_bf16 v[100:103], v[160:163], v[194:197], v[100:103]
	v_mfma_f32_16x16x32_bf16 v[104:107], v[160:163], v[198:201], v[104:107]
	v_mfma_f32_16x16x32_bf16 v[96:99], v[160:163], v[202:205], v[96:99]
	v_mfma_f32_16x16x32_bf16 v[92:95], v[164:167], v[190:193], v[92:95]
	v_mfma_f32_16x16x32_bf16 v[84:87], v[164:167], v[194:197], v[84:87]
	v_mfma_f32_16x16x32_bf16 v[88:91], v[164:167], v[198:201], v[88:91]
	v_mfma_f32_16x16x32_bf16 v[80:83], v[164:167], v[202:205], v[80:83]
	v_mfma_f32_16x16x32_bf16 v[76:79], v[168:171], v[190:193], v[76:79]
	v_mfma_f32_16x16x32_bf16 v[68:71], v[168:171], v[194:197], v[68:71]
	v_mfma_f32_16x16x32_bf16 v[72:75], v[168:171], v[198:201], v[72:75]
	v_mfma_f32_16x16x32_bf16 v[64:67], v[168:171], v[202:205], v[64:67]
	ds_read_b128 v[156:159], v224
	ds_read_b128 v[160:163], v224 offset:2048
	ds_read_b128 v[164:167], v224 offset:4096
	ds_read_b128 v[168:171], v224 offset:6144
	ds_read_b128 v[206:209], v226 offset:32768
	ds_read_b128 v[210:213], v226 offset:34816
	ds_read_b128 v[214:217], v226 offset:36864
	ds_read_b128 v[218:221], v226 offset:38912
	s_waitcnt lgkmcnt(8)
	v_mfma_f32_16x16x32_bf16 v[60:63], v[172:175], v[190:193], v[60:63]
	v_mfma_f32_16x16x32_bf16 v[52:55], v[172:175], v[194:197], v[52:55]
	v_mfma_f32_16x16x32_bf16 v[56:59], v[172:175], v[198:201], v[56:59]
	v_mfma_f32_16x16x32_bf16 v[48:51], v[172:175], v[202:205], v[48:51]
	v_mfma_f32_16x16x32_bf16 v[44:47], v[176:179], v[190:193], v[44:47]
	v_mfma_f32_16x16x32_bf16 v[36:39], v[176:179], v[194:197], v[36:39]
	v_mfma_f32_16x16x32_bf16 v[40:43], v[176:179], v[198:201], v[40:43]
	v_mfma_f32_16x16x32_bf16 v[32:35], v[176:179], v[202:205], v[32:35]
	v_mfma_f32_16x16x32_bf16 v[28:31], v[182:185], v[190:193], v[28:31]
	v_mfma_f32_16x16x32_bf16 v[16:19], v[182:185], v[194:197], v[16:19]
	v_mfma_f32_16x16x32_bf16 v[24:27], v[182:185], v[198:201], v[24:27]
	v_mfma_f32_16x16x32_bf16 v[12:15], v[182:185], v[202:205], v[12:15]
	v_mfma_f32_16x16x32_bf16 v[4:7], v[186:189], v[190:193], v[4:7]
	v_mfma_f32_16x16x32_bf16 v[0:3], v[186:189], v[194:197], v[0:3]
	v_mfma_f32_16x16x32_bf16 v[20:23], v[186:189], v[198:201], v[20:23]
	v_mfma_f32_16x16x32_bf16 v[8:11], v[186:189], v[202:205], v[8:11]
	ds_read_b128 v[172:175], v224 offset:8192
	ds_read_b128 v[176:179], v224 offset:10240
	ds_read_b128 v[182:185], v224 offset:12288
	ds_read_b128 v[186:189], v224 offset:14336
	s_waitcnt lgkmcnt(4)
	v_mfma_f32_16x16x32_bf16 v[124:127], v[156:159], v[206:209], v[124:127]
	v_mfma_f32_16x16x32_bf16 v[116:119], v[156:159], v[210:213], v[116:119]
	v_mfma_f32_16x16x32_bf16 v[120:123], v[156:159], v[214:217], v[120:123]
	v_mfma_f32_16x16x32_bf16 v[112:115], v[156:159], v[218:221], v[112:115]
	v_mfma_f32_16x16x32_bf16 v[108:111], v[160:163], v[206:209], v[108:111]
	v_mfma_f32_16x16x32_bf16 v[100:103], v[160:163], v[210:213], v[100:103]
	v_mfma_f32_16x16x32_bf16 v[104:107], v[160:163], v[214:217], v[104:107]
	v_mfma_f32_16x16x32_bf16 v[96:99], v[160:163], v[218:221], v[96:99]
	v_mfma_f32_16x16x32_bf16 v[92:95], v[164:167], v[206:209], v[92:95]
	v_mfma_f32_16x16x32_bf16 v[84:87], v[164:167], v[210:213], v[84:87]
	v_mfma_f32_16x16x32_bf16 v[88:91], v[164:167], v[214:217], v[88:91]
	v_mfma_f32_16x16x32_bf16 v[80:83], v[164:167], v[218:221], v[80:83]
	v_mfma_f32_16x16x32_bf16 v[76:79], v[168:171], v[206:209], v[76:79]
	v_mfma_f32_16x16x32_bf16 v[68:71], v[168:171], v[210:213], v[68:71]
	v_mfma_f32_16x16x32_bf16 v[72:75], v[168:171], v[214:217], v[72:75]
	v_mfma_f32_16x16x32_bf16 v[64:67], v[168:171], v[218:221], v[64:67]
	s_add_u32 s60, s60, 0x80
	s_addc_u32 s61, s61, 0
	s_add_i32 s59, s59, 1
	s_branch .Lg0_top

.Lg1_top:
	s_waitcnt lgkmcnt(0)
	s_waitcnt vmcnt(0)
	s_barrier
	s_xor_b32 s59, s59, 0x10000
	s_mov_b32 m0, s59
	s_add_u32 s52, s50, s14
	s_addc_u32 s53, s51, s15
	global_load_lds_dwordx4 v178, s[52:53]
	s_add_u32 m0, s59, 0x2000
	s_add_u32 s52, s50, s16
	s_addc_u32 s53, s51, s17
	global_load_lds_dwordx4 v178, s[52:53]
	ds_read_b128 v[142:145], v141
	ds_read_b128 v[146:149], v141 offset:2048
	ds_read_b128 v[150:153], v141 offset:4096
	ds_read_b128 v[154:157], v141 offset:6144
	ds_read_b128 v[174:177], v210 offset:32768
	ds_read_b128 v[182:185], v210 offset:34816
	ds_read_b128 v[186:189], v210 offset:36864
	ds_read_b128 v[190:193], v210 offset:38912
	v_mfma_f32_16x16x32_bf16 v[60:63], v[158:161], v[194:197], v[60:63]
	v_mfma_f32_16x16x32_bf16 v[56:59], v[158:161], v[198:201], v[56:59]
	s_add_u32 m0, s59, 0x4000
	s_add_u32 s52, s50, s18
	s_addc_u32 s53, s51, s19
	global_load_lds_dwordx4 v178, s[52:53]
	v_mfma_f32_16x16x32_bf16 v[52:55], v[158:161], v[202:205], v[52:55]
	v_mfma_f32_16x16x32_bf16 v[48:51], v[158:161], v[206:209], v[48:51]
	s_add_u32 m0, s59, 0x6000
	s_add_u32 s52, s50, s22
	s_addc_u32 s53, s51, s23
	global_load_lds_dwordx4 v178, s[52:53]
	v_mfma_f32_16x16x32_bf16 v[44:47], v[162:165], v[194:197], v[44:47]
	v_mfma_f32_16x16x32_bf16 v[40:43], v[162:165], v[198:201], v[40:43]
	s_add_u32 m0, s59, 0x8000
	s_add_u32 s52, s50, s40
	s_addc_u32 s53, s51, s41
	global_load_lds_dwordx4 v179, s[52:53]
	v_mfma_f32_16x16x32_bf16 v[36:39], v[162:165], v[202:205], v[36:39]
	v_mfma_f32_16x16x32_bf16 v[32:35], v[162:165], v[206:209], v[32:35]
	s_add_u32 m0, s59, 0xa000
	s_add_u32 s52, s50, s42
	s_addc_u32 s53, s51, s43
	global_load_lds_dwordx4 v179, s[52:53]
	v_mfma_f32_16x16x32_bf16 v[28:31], v[166:169], v[194:197], v[28:31]
	v_mfma_f32_16x16x32_bf16 v[20:23], v[166:169], v[198:201], v[20:23]
	s_add_u32 m0, s59, 0xc000
	s_add_u32 s52, s50, s44
	s_addc_u32 s53, s51, s45
	global_load_lds_dwordx4 v179, s[52:53]
	v_mfma_f32_16x16x32_bf16 v[16:19], v[166:169], v[202:205], v[16:19]
	v_mfma_f32_16x16x32_bf16 v[8:11], v[166:169], v[206:209], v[8:11]
	s_add_u32 m0, s59, 0xe000
	s_add_u32 s52, s50, s46
	s_addc_u32 s53, s51, s47
	global_load_lds_dwordx4 v179, s[52:53]
	v_mfma_f32_16x16x32_bf16 v[4:7], v[170:173], v[194:197], v[4:7]
	v_mfma_f32_16x16x32_bf16 v[0:3], v[170:173], v[198:201], v[0:3]
	v_mfma_f32_16x16x32_bf16 v[24:27], v[170:173], v[202:205], v[24:27]
	v_mfma_f32_16x16x32_bf16 v[12:15], v[170:173], v[206:209], v[12:15]
.Lg1_entry:
	ds_read_b128 v[158:161], v141 offset:8192
	ds_read_b128 v[162:165], v141 offset:10240
	ds_read_b128 v[166:169], v141 offset:12288
	ds_read_b128 v[170:173], v141 offset:14336
	s_waitcnt lgkmcnt(4)
	v_mfma_f32_16x16x32_bf16 v[124:127], v[142:145], v[174:177], v[124:127]
	v_mfma_f32_16x16x32_bf16 v[120:123], v[142:145], v[182:185], v[120:123]
	v_mfma_f32_16x16x32_bf16 v[116:119], v[142:145], v[186:189], v[116:119]
	v_mfma_f32_16x16x32_bf16 v[112:115], v[142:145], v[190:193], v[112:115]
	v_mfma_f32_16x16x32_bf16 v[108:111], v[146:149], v[174:177], v[108:111]
	v_mfma_f32_16x16x32_bf16 v[104:107], v[146:149], v[182:185], v[104:107]
	v_mfma_f32_16x16x32_bf16 v[100:103], v[146:149], v[186:189], v[100:103]
	v_mfma_f32_16x16x32_bf16 v[96:99], v[146:149], v[190:193], v[96:99]
	v_mfma_f32_16x16x32_bf16 v[92:95], v[150:153], v[174:177], v[92:95]
	v_mfma_f32_16x16x32_bf16 v[88:91], v[150:153], v[182:185], v[88:91]
	v_mfma_f32_16x16x32_bf16 v[84:87], v[150:153], v[186:189], v[84:87]
	v_mfma_f32_16x16x32_bf16 v[80:83], v[150:153], v[190:193], v[80:83]
	v_mfma_f32_16x16x32_bf16 v[76:79], v[154:157], v[174:177], v[76:79]
	v_mfma_f32_16x16x32_bf16 v[72:75], v[154:157], v[182:185], v[72:75]
	v_mfma_f32_16x16x32_bf16 v[68:71], v[154:157], v[186:189], v[68:71]
	v_mfma_f32_16x16x32_bf16 v[64:67], v[154:157], v[190:193], v[64:67]
	ds_read_b128 v[142:145], v180
	ds_read_b128 v[146:149], v180 offset:2048
	ds_read_b128 v[150:153], v180 offset:4096
	ds_read_b128 v[154:157], v180 offset:6144
	ds_read_b128 v[194:197], v211 offset:32768
	ds_read_b128 v[198:201], v211 offset:34816
	ds_read_b128 v[202:205], v211 offset:36864
	ds_read_b128 v[206:209], v211 offset:38912
	s_waitcnt lgkmcnt(8)
	v_mfma_f32_16x16x32_bf16 v[60:63], v[158:161], v[174:177], v[60:63]
	v_mfma_f32_16x16x32_bf16 v[56:59], v[158:161], v[182:185], v[56:59]
	v_mfma_f32_16x16x32_bf16 v[52:55], v[158:161], v[186:189], v[52:55]
	v_mfma_f32_16x16x32_bf16 v[48:51], v[158:161], v[190:193], v[48:51]
	v_mfma_f32_16x16x32_bf16 v[44:47], v[162:165], v[174:177], v[44:47]
	v_mfma_f32_16x16x32_bf16 v[40:43], v[162:165], v[182:185], v[40:43]
	v_mfma_f32_16x16x32_bf16 v[36:39], v[162:165], v[186:189], v[36:39]
	v_mfma_f32_16x16x32_bf16 v[32:35], v[162:165], v[190:193], v[32:35]
	v_mfma_f32_16x16x32_bf16 v[28:31], v[166:169], v[174:177], v[28:31]
	v_mfma_f32_16x16x32_bf16 v[20:23], v[166:169], v[182:185], v[20:23]
	v_mfma_f32_16x16x32_bf16 v[16:19], v[166:169], v[186:189], v[16:19]
	v_mfma_f32_16x16x32_bf16 v[8:11], v[166:169], v[190:193], v[8:11]
	v_mfma_f32_16x16x32_bf16 v[4:7], v[170:173], v[174:177], v[4:7]
	v_mfma_f32_16x16x32_bf16 v[0:3], v[170:173], v[182:185], v[0:3]
	v_mfma_f32_16x16x32_bf16 v[24:27], v[170:173], v[186:189], v[24:27]
	v_mfma_f32_16x16x32_bf16 v[12:15], v[170:173], v[190:193], v[12:15]
	ds_read_b128 v[158:161], v180 offset:8192
	ds_read_b128 v[162:165], v180 offset:10240
	ds_read_b128 v[166:169], v180 offset:12288
	ds_read_b128 v[170:173], v180 offset:14336
	s_waitcnt lgkmcnt(4)
	v_mfma_f32_16x16x32_bf16 v[124:127], v[142:145], v[194:197], v[124:127]
	v_mfma_f32_16x16x32_bf16 v[120:123], v[142:145], v[198:201], v[120:123]
	v_mfma_f32_16x16x32_bf16 v[116:119], v[142:145], v[202:205], v[116:119]
	v_mfma_f32_16x16x32_bf16 v[112:115], v[142:145], v[206:209], v[112:115]
	v_mfma_f32_16x16x32_bf16 v[108:111], v[146:149], v[194:197], v[108:111]
	v_mfma_f32_16x16x32_bf16 v[104:107], v[146:149], v[198:201], v[104:107]
	v_mfma_f32_16x16x32_bf16 v[100:103], v[146:149], v[202:205], v[100:103]
	v_mfma_f32_16x16x32_bf16 v[96:99], v[146:149], v[206:209], v[96:99]
	v_mfma_f32_16x16x32_bf16 v[92:95], v[150:153], v[194:197], v[92:95]
	v_mfma_f32_16x16x32_bf16 v[88:91], v[150:153], v[198:201], v[88:91]
	v_mfma_f32_16x16x32_bf16 v[84:87], v[150:153], v[202:205], v[84:87]
	v_mfma_f32_16x16x32_bf16 v[80:83], v[150:153], v[206:209], v[80:83]
	v_mfma_f32_16x16x32_bf16 v[76:79], v[154:157], v[194:197], v[76:79]
	v_mfma_f32_16x16x32_bf16 v[72:75], v[154:157], v[198:201], v[72:75]
	v_mfma_f32_16x16x32_bf16 v[68:71], v[154:157], v[202:205], v[68:71]
	v_mfma_f32_16x16x32_bf16 v[64:67], v[154:157], v[206:209], v[64:67]
	s_add_u32 s50, s50, 0x80
	s_addc_u32 s51, s51, 0
	s_add_i32 s49, s49, 1
	s_cmp_lt_u32 s49, 31
	s_cbranch_scc0 .Lg1_last
	s_waitcnt lgkmcnt(0)
	s_waitcnt vmcnt(0)
	s_barrier
	s_xor_b32 s59, s59, 0x10000
	s_mov_b32 m0, s59
	s_add_u32 s52, s50, s14
	s_addc_u32 s53, s51, s15
	global_load_lds_dwordx4 v178, s[52:53]
	s_add_u32 m0, s59, 0x2000
	s_add_u32 s52, s50, s16
	s_addc_u32 s53, s51, s17
	global_load_lds_dwordx4 v178, s[52:53]
	ds_read_b128 v[142:145], v212
	ds_read_b128 v[146:149], v212 offset:2048
	ds_read_b128 v[150:153], v212 offset:4096
	ds_read_b128 v[154:157], v212 offset:6144
	ds_read_b128 v[174:177], v214 offset:32768
	ds_read_b128 v[182:185], v214 offset:34816
	ds_read_b128 v[186:189], v214 offset:36864
	ds_read_b128 v[190:193], v214 offset:38912
	v_mfma_f32_16x16x32_bf16 v[60:63], v[158:161], v[194:197], v[60:63]
	v_mfma_f32_16x16x32_bf16 v[56:59], v[158:161], v[198:201], v[56:59]
	s_add_u32 m0, s59, 0x4000
	s_add_u32 s52, s50, s18
	s_addc_u32 s53, s51, s19
	global_load_lds_dwordx4 v178, s[52:53]
	v_mfma_f32_16x16x32_bf16 v[52:55], v[158:161], v[202:205], v[52:55]
	v_mfma_f32_16x16x32_bf16 v[48:51], v[158:161], v[206:209], v[48:51]
	s_add_u32 m0, s59, 0x6000
	s_add_u32 s52, s50, s22
	s_addc_u32 s53, s51, s23
	global_load_lds_dwordx4 v178, s[52:53]
	v_mfma_f32_16x16x32_bf16 v[44:47], v[162:165], v[194:197], v[44:47]
	v_mfma_f32_16x16x32_bf16 v[40:43], v[162:165], v[198:201], v[40:43]
	s_add_u32 m0, s59, 0x8000
	s_add_u32 s52, s50, s40
	s_addc_u32 s53, s51, s41
	global_load_lds_dwordx4 v179, s[52:53]
	v_mfma_f32_16x16x32_bf16 v[36:39], v[162:165], v[202:205], v[36:39]
	v_mfma_f32_16x16x32_bf16 v[32:35], v[162:165], v[206:209], v[32:35]
	s_add_u32 m0, s59, 0xa000
	s_add_u32 s52, s50, s42
	s_addc_u32 s53, s51, s43
	global_load_lds_dwordx4 v179, s[52:53]
	v_mfma_f32_16x16x32_bf16 v[28:31], v[166:169], v[194:197], v[28:31]
	v_mfma_f32_16x16x32_bf16 v[20:23], v[166:169], v[198:201], v[20:23]
	s_add_u32 m0, s59, 0xc000
	s_add_u32 s52, s50, s44
	s_addc_u32 s53, s51, s45
	global_load_lds_dwordx4 v179, s[52:53]
	v_mfma_f32_16x16x32_bf16 v[16:19], v[166:169], v[202:205], v[16:19]
	v_mfma_f32_16x16x32_bf16 v[8:11], v[166:169], v[206:209], v[8:11]
	s_add_u32 m0, s59, 0xe000
	s_add_u32 s52, s50, s46
	s_addc_u32 s53, s51, s47
	global_load_lds_dwordx4 v179, s[52:53]
	v_mfma_f32_16x16x32_bf16 v[4:7], v[170:173], v[194:197], v[4:7]
	v_mfma_f32_16x16x32_bf16 v[0:3], v[170:173], v[198:201], v[0:3]
	v_mfma_f32_16x16x32_bf16 v[24:27], v[170:173], v[202:205], v[24:27]
	v_mfma_f32_16x16x32_bf16 v[12:15], v[170:173], v[206:209], v[12:15]
	ds_read_b128 v[158:161], v212 offset:8192
	ds_read_b128 v[162:165], v212 offset:10240
	ds_read_b128 v[166:169], v212 offset:12288
	ds_read_b128 v[170:173], v212 offset:14336
	s_waitcnt lgkmcnt(4)
	v_mfma_f32_16x16x32_bf16 v[124:127], v[142:145], v[174:177], v[124:127]
	v_mfma_f32_16x16x32_bf16 v[120:123], v[142:145], v[182:185], v[120:123]
	v_mfma_f32_16x16x32_bf16 v[116:119], v[142:145], v[186:189], v[116:119]
	v_mfma_f32_16x16x32_bf16 v[112:115], v[142:145], v[190:193], v[112:115]
	v_mfma_f32_16x16x32_bf16 v[108:111], v[146:149], v[174:177], v[108:111]
	v_mfma_f32_16x16x32_bf16 v[104:107], v[146:149], v[182:185], v[104:107]
	v_mfma_f32_16x16x32_bf16 v[100:103], v[146:149], v[186:189], v[100:103]
	v_mfma_f32_16x16x32_bf16 v[96:99], v[146:149], v[190:193], v[96:99]
	v_mfma_f32_16x16x32_bf16 v[92:95], v[150:153], v[174:177], v[92:95]
	v_mfma_f32_16x16x32_bf16 v[88:91], v[150:153], v[182:185], v[88:91]
	v_mfma_f32_16x16x32_bf16 v[84:87], v[150:153], v[186:189], v[84:87]
	v_mfma_f32_16x16x32_bf16 v[80:83], v[150:153], v[190:193], v[80:83]
	v_mfma_f32_16x16x32_bf16 v[76:79], v[154:157], v[174:177], v[76:79]
	v_mfma_f32_16x16x32_bf16 v[72:75], v[154:157], v[182:185], v[72:75]
	v_mfma_f32_16x16x32_bf16 v[68:71], v[154:157], v[186:189], v[68:71]
	v_mfma_f32_16x16x32_bf16 v[64:67], v[154:157], v[190:193], v[64:67]
	ds_read_b128 v[142:145], v213
	ds_read_b128 v[146:149], v213 offset:2048
	ds_read_b128 v[150:153], v213 offset:4096
	ds_read_b128 v[154:157], v213 offset:6144
	ds_read_b128 v[194:197], v215 offset:32768
	ds_read_b128 v[198:201], v215 offset:34816
	ds_read_b128 v[202:205], v215 offset:36864
	ds_read_b128 v[206:209], v215 offset:38912
	s_waitcnt lgkmcnt(8)
	v_mfma_f32_16x16x32_bf16 v[60:63], v[158:161], v[174:177], v[60:63]
	v_mfma_f32_16x16x32_bf16 v[56:59], v[158:161], v[182:185], v[56:59]
	v_mfma_f32_16x16x32_bf16 v[52:55], v[158:161], v[186:189], v[52:55]
	v_mfma_f32_16x16x32_bf16 v[48:51], v[158:161], v[190:193], v[48:51]
	v_mfma_f32_16x16x32_bf16 v[44:47], v[162:165], v[174:177], v[44:47]
	v_mfma_f32_16x16x32_bf16 v[40:43], v[162:165], v[182:185], v[40:43]
	v_mfma_f32_16x16x32_bf16 v[36:39], v[162:165], v[186:189], v[36:39]
	v_mfma_f32_16x16x32_bf16 v[32:35], v[162:165], v[190:193], v[32:35]
	v_mfma_f32_16x16x32_bf16 v[28:31], v[166:169], v[174:177], v[28:31]
	v_mfma_f32_16x16x32_bf16 v[20:23], v[166:169], v[182:185], v[20:23]
	v_mfma_f32_16x16x32_bf16 v[16:19], v[166:169], v[186:189], v[16:19]
	v_mfma_f32_16x16x32_bf16 v[8:11], v[166:169], v[190:193], v[8:11]
	v_mfma_f32_16x16x32_bf16 v[4:7], v[170:173], v[174:177], v[4:7]
	v_mfma_f32_16x16x32_bf16 v[0:3], v[170:173], v[182:185], v[0:3]
	v_mfma_f32_16x16x32_bf16 v[24:27], v[170:173], v[186:189], v[24:27]
	v_mfma_f32_16x16x32_bf16 v[12:15], v[170:173], v[190:193], v[12:15]
	ds_read_b128 v[158:161], v213 offset:8192
	ds_read_b128 v[162:165], v213 offset:10240
	ds_read_b128 v[166:169], v213 offset:12288
	ds_read_b128 v[170:173], v213 offset:14336
	s_waitcnt lgkmcnt(4)
	v_mfma_f32_16x16x32_bf16 v[124:127], v[142:145], v[194:197], v[124:127]
	v_mfma_f32_16x16x32_bf16 v[120:123], v[142:145], v[198:201], v[120:123]
	v_mfma_f32_16x16x32_bf16 v[116:119], v[142:145], v[202:205], v[116:119]
	v_mfma_f32_16x16x32_bf16 v[112:115], v[142:145], v[206:209], v[112:115]
	v_mfma_f32_16x16x32_bf16 v[108:111], v[146:149], v[194:197], v[108:111]
	v_mfma_f32_16x16x32_bf16 v[104:107], v[146:149], v[198:201], v[104:107]
	v_mfma_f32_16x16x32_bf16 v[100:103], v[146:149], v[202:205], v[100:103]
	v_mfma_f32_16x16x32_bf16 v[96:99], v[146:149], v[206:209], v[96:99]
	v_mfma_f32_16x16x32_bf16 v[92:95], v[150:153], v[194:197], v[92:95]
	v_mfma_f32_16x16x32_bf16 v[88:91], v[150:153], v[198:201], v[88:91]
	v_mfma_f32_16x16x32_bf16 v[84:87], v[150:153], v[202:205], v[84:87]
	v_mfma_f32_16x16x32_bf16 v[80:83], v[150:153], v[206:209], v[80:83]
	v_mfma_f32_16x16x32_bf16 v[76:79], v[154:157], v[194:197], v[76:79]
	v_mfma_f32_16x16x32_bf16 v[72:75], v[154:157], v[198:201], v[72:75]
	v_mfma_f32_16x16x32_bf16 v[68:71], v[154:157], v[202:205], v[68:71]
	v_mfma_f32_16x16x32_bf16 v[64:67], v[154:157], v[206:209], v[64:67]
	s_add_u32 s50, s50, 0x80
	s_addc_u32 s51, s51, 0
	s_add_i32 s49, s49, 1
	s_branch .Lg1_top

.Lg2_top:
	s_waitcnt lgkmcnt(0)
	s_waitcnt vmcnt(0)
	s_barrier
	s_xor_b32 s62, s62, 0x10000
	s_mov_b32 m0, s62
	s_add_u32 s50, s48, s12
	s_addc_u32 s51, s49, s13
	global_load_lds_dwordx4 v178, s[50:51]
	s_add_u32 m0, s62, 0x2000
	s_add_u32 s50, s48, s14
	s_addc_u32 s51, s49, s15
	global_load_lds_dwordx4 v178, s[50:51]
	ds_read_b128 v[146:149], v180
	ds_read_b128 v[150:153], v180 offset:2048
	ds_read_b128 v[154:157], v180 offset:4096
	ds_read_b128 v[158:161], v180 offset:6144
	ds_read_b128 v[182:185], v215 offset:32768
	ds_read_b128 v[186:189], v215 offset:34816
	ds_read_b128 v[190:193], v215 offset:36864
	ds_read_b128 v[194:197], v215 offset:38912
	v_mfma_f32_16x16x32_bf16 v[60:63], v[162:165], v[198:201], v[60:63]
	v_mfma_f32_16x16x32_bf16 v[56:59], v[162:165], v[202:205], v[56:59]
	s_add_u32 m0, s62, 0x4000
	s_add_u32 s50, s48, s16
	s_addc_u32 s51, s49, s17
	global_load_lds_dwordx4 v178, s[50:51]
	v_mfma_f32_16x16x32_bf16 v[52:55], v[162:165], v[206:209], v[52:55]
	v_mfma_f32_16x16x32_bf16 v[44:47], v[162:165], v[210:213], v[44:47]
	s_add_u32 m0, s62, 0x6000
	s_add_u32 s50, s48, s18
	s_addc_u32 s51, s49, s19
	global_load_lds_dwordx4 v178, s[50:51]
	v_mfma_f32_16x16x32_bf16 v[36:39], v[166:169], v[198:201], v[36:39]
	v_mfma_f32_16x16x32_bf16 v[32:35], v[166:169], v[202:205], v[32:35]
	s_add_u32 m0, s62, 0x8000
	s_add_u32 s50, s48, s22
	s_addc_u32 s51, s49, s23
	global_load_lds_dwordx4 v179, s[50:51]
	v_mfma_f32_16x16x32_bf16 v[28:31], v[166:169], v[206:209], v[28:31]
	v_mfma_f32_16x16x32_bf16 v[24:27], v[166:169], v[210:213], v[24:27]
	s_add_u32 m0, s62, 0xa000
	s_add_u32 s50, s48, s36
	s_addc_u32 s51, s49, s37
	global_load_lds_dwordx4 v179, s[50:51]
	v_mfma_f32_16x16x32_bf16 v[20:23], v[170:173], v[198:201], v[20:23]
	v_mfma_f32_16x16x32_bf16 v[16:19], v[170:173], v[202:205], v[16:19]
	s_add_u32 m0, s62, 0xc000
	s_add_u32 s50, s48, s40
	s_addc_u32 s51, s49, s41
	global_load_lds_dwordx4 v179, s[50:51]
	v_mfma_f32_16x16x32_bf16 v[12:15], v[170:173], v[206:209], v[12:15]
	v_mfma_f32_16x16x32_bf16 v[8:11], v[170:173], v[210:213], v[8:11]
	s_add_u32 m0, s62, 0xe000
	s_add_u32 s50, s48, s42
	s_addc_u32 s51, s49, s43
	global_load_lds_dwordx4 v179, s[50:51]
	v_mfma_f32_16x16x32_bf16 v[4:7], v[174:177], v[198:201], v[4:7]
	v_mfma_f32_16x16x32_bf16 v[0:3], v[174:177], v[202:205], v[0:3]
	v_mfma_f32_16x16x32_bf16 v[48:51], v[174:177], v[206:209], v[48:51]
	v_mfma_f32_16x16x32_bf16 v[40:43], v[174:177], v[210:213], v[40:43]
.Lg2_entry:
	ds_read_b128 v[162:165], v180 offset:8192
	ds_read_b128 v[166:169], v180 offset:10240
	ds_read_b128 v[170:173], v180 offset:12288
	ds_read_b128 v[174:177], v180 offset:14336
	s_waitcnt lgkmcnt(4)
	v_mfma_f32_16x16x32_bf16 v[124:127], v[146:149], v[182:185], v[124:127]
	v_mfma_f32_16x16x32_bf16 v[120:123], v[146:149], v[186:189], v[120:123]
	v_mfma_f32_16x16x32_bf16 v[116:119], v[146:149], v[190:193], v[116:119]
	v_mfma_f32_16x16x32_bf16 v[112:115], v[146:149], v[194:197], v[112:115]
	v_mfma_f32_16x16x32_bf16 v[108:111], v[150:153], v[182:185], v[108:111]
	v_mfma_f32_16x16x32_bf16 v[104:107], v[150:153], v[186:189], v[104:107]
	v_mfma_f32_16x16x32_bf16 v[100:103], v[150:153], v[190:193], v[100:103]
	v_mfma_f32_16x16x32_bf16 v[96:99], v[150:153], v[194:197], v[96:99]
	v_mfma_f32_16x16x32_bf16 v[92:95], v[154:157], v[182:185], v[92:95]
	v_mfma_f32_16x16x32_bf16 v[88:91], v[154:157], v[186:189], v[88:91]
	v_mfma_f32_16x16x32_bf16 v[84:87], v[154:157], v[190:193], v[84:87]
	v_mfma_f32_16x16x32_bf16 v[80:83], v[154:157], v[194:197], v[80:83]
	v_mfma_f32_16x16x32_bf16 v[76:79], v[158:161], v[182:185], v[76:79]
	v_mfma_f32_16x16x32_bf16 v[72:75], v[158:161], v[186:189], v[72:75]
	v_mfma_f32_16x16x32_bf16 v[68:71], v[158:161], v[190:193], v[68:71]
	v_mfma_f32_16x16x32_bf16 v[64:67], v[158:161], v[194:197], v[64:67]
	ds_read_b128 v[146:149], v214
	ds_read_b128 v[150:153], v214 offset:2048
	ds_read_b128 v[154:157], v214 offset:4096
	ds_read_b128 v[158:161], v214 offset:6144
	ds_read_b128 v[198:201], v216 offset:32768
	ds_read_b128 v[202:205], v216 offset:34816
	ds_read_b128 v[206:209], v216 offset:36864
	ds_read_b128 v[210:213], v216 offset:38912
	s_waitcnt lgkmcnt(8)
	v_mfma_f32_16x16x32_bf16 v[60:63], v[162:165], v[182:185], v[60:63]
	v_mfma_f32_16x16x32_bf16 v[56:59], v[162:165], v[186:189], v[56:59]
	v_mfma_f32_16x16x32_bf16 v[52:55], v[162:165], v[190:193], v[52:55]
	v_mfma_f32_16x16x32_bf16 v[44:47], v[162:165], v[194:197], v[44:47]
	v_mfma_f32_16x16x32_bf16 v[36:39], v[166:169], v[182:185], v[36:39]
	v_mfma_f32_16x16x32_bf16 v[32:35], v[166:169], v[186:189], v[32:35]
	v_mfma_f32_16x16x32_bf16 v[28:31], v[166:169], v[190:193], v[28:31]
	v_mfma_f32_16x16x32_bf16 v[24:27], v[166:169], v[194:197], v[24:27]
	v_mfma_f32_16x16x32_bf16 v[20:23], v[170:173], v[182:185], v[20:23]
	v_mfma_f32_16x16x32_bf16 v[16:19], v[170:173], v[186:189], v[16:19]
	v_mfma_f32_16x16x32_bf16 v[12:15], v[170:173], v[190:193], v[12:15]
	v_mfma_f32_16x16x32_bf16 v[8:11], v[170:173], v[194:197], v[8:11]
	v_mfma_f32_16x16x32_bf16 v[4:7], v[174:177], v[182:185], v[4:7]
	v_mfma_f32_16x16x32_bf16 v[0:3], v[174:177], v[186:189], v[0:3]
	v_mfma_f32_16x16x32_bf16 v[48:51], v[174:177], v[190:193], v[48:51]
	v_mfma_f32_16x16x32_bf16 v[40:43], v[174:177], v[194:197], v[40:43]
	ds_read_b128 v[162:165], v214 offset:8192
	ds_read_b128 v[166:169], v214 offset:10240
	ds_read_b128 v[170:173], v214 offset:12288
	ds_read_b128 v[174:177], v214 offset:14336
	s_waitcnt lgkmcnt(4)
	v_mfma_f32_16x16x32_bf16 v[124:127], v[146:149], v[198:201], v[124:127]
	v_mfma_f32_16x16x32_bf16 v[120:123], v[146:149], v[202:205], v[120:123]
	v_mfma_f32_16x16x32_bf16 v[116:119], v[146:149], v[206:209], v[116:119]
	v_mfma_f32_16x16x32_bf16 v[112:115], v[146:149], v[210:213], v[112:115]
	v_mfma_f32_16x16x32_bf16 v[108:111], v[150:153], v[198:201], v[108:111]
	v_mfma_f32_16x16x32_bf16 v[104:107], v[150:153], v[202:205], v[104:107]
	v_mfma_f32_16x16x32_bf16 v[100:103], v[150:153], v[206:209], v[100:103]
	v_mfma_f32_16x16x32_bf16 v[96:99], v[150:153], v[210:213], v[96:99]
	v_mfma_f32_16x16x32_bf16 v[92:95], v[154:157], v[198:201], v[92:95]
	v_mfma_f32_16x16x32_bf16 v[88:91], v[154:157], v[202:205], v[88:91]
	v_mfma_f32_16x16x32_bf16 v[84:87], v[154:157], v[206:209], v[84:87]
	v_mfma_f32_16x16x32_bf16 v[80:83], v[154:157], v[210:213], v[80:83]
	v_mfma_f32_16x16x32_bf16 v[76:79], v[158:161], v[198:201], v[76:79]
	v_mfma_f32_16x16x32_bf16 v[72:75], v[158:161], v[202:205], v[72:75]
	v_mfma_f32_16x16x32_bf16 v[68:71], v[158:161], v[206:209], v[68:71]
	v_mfma_f32_16x16x32_bf16 v[64:67], v[158:161], v[210:213], v[64:67]
	s_add_u32 s48, s48, 0x80
	s_addc_u32 s49, s49, 0
	s_add_i32 s47, s47, 1
	s_cmp_lt_u32 s47, 15
	s_cbranch_scc0 .Lg2_last
	s_waitcnt lgkmcnt(0)
	s_waitcnt vmcnt(0)
	s_barrier
	s_xor_b32 s62, s62, 0x10000
	s_mov_b32 m0, s62
	s_add_u32 s50, s48, s12
	s_addc_u32 s51, s49, s13
	global_load_lds_dwordx4 v178, s[50:51]
	s_add_u32 m0, s62, 0x2000
	s_add_u32 s50, s48, s14
	s_addc_u32 s51, s49, s15
	global_load_lds_dwordx4 v178, s[50:51]
	ds_read_b128 v[146:149], v217
	ds_read_b128 v[150:153], v217 offset:2048
	ds_read_b128 v[154:157], v217 offset:4096
	ds_read_b128 v[158:161], v217 offset:6144
	ds_read_b128 v[182:185], v219 offset:32768
	ds_read_b128 v[186:189], v219 offset:34816
	ds_read_b128 v[190:193], v219 offset:36864
	ds_read_b128 v[194:197], v219 offset:38912
	v_mfma_f32_16x16x32_bf16 v[60:63], v[162:165], v[198:201], v[60:63]
	v_mfma_f32_16x16x32_bf16 v[56:59], v[162:165], v[202:205], v[56:59]
	s_add_u32 m0, s62, 0x4000
	s_add_u32 s50, s48, s16
	s_addc_u32 s51, s49, s17
	global_load_lds_dwordx4 v178, s[50:51]
	v_mfma_f32_16x16x32_bf16 v[52:55], v[162:165], v[206:209], v[52:55]
	v_mfma_f32_16x16x32_bf16 v[44:47], v[162:165], v[210:213], v[44:47]
	s_add_u32 m0, s62, 0x6000
	s_add_u32 s50, s48, s18
	s_addc_u32 s51, s49, s19
	global_load_lds_dwordx4 v178, s[50:51]
	v_mfma_f32_16x16x32_bf16 v[36:39], v[166:169], v[198:201], v[36:39]
	v_mfma_f32_16x16x32_bf16 v[32:35], v[166:169], v[202:205], v[32:35]
	s_add_u32 m0, s62, 0x8000
	s_add_u32 s50, s48, s22
	s_addc_u32 s51, s49, s23
	global_load_lds_dwordx4 v179, s[50:51]
	v_mfma_f32_16x16x32_bf16 v[28:31], v[166:169], v[206:209], v[28:31]
	v_mfma_f32_16x16x32_bf16 v[24:27], v[166:169], v[210:213], v[24:27]
	s_add_u32 m0, s62, 0xa000
	s_add_u32 s50, s48, s36
	s_addc_u32 s51, s49, s37
	global_load_lds_dwordx4 v179, s[50:51]
	v_mfma_f32_16x16x32_bf16 v[20:23], v[170:173], v[198:201], v[20:23]
	v_mfma_f32_16x16x32_bf16 v[16:19], v[170:173], v[202:205], v[16:19]
	s_add_u32 m0, s62, 0xc000
	s_add_u32 s50, s48, s40
	s_addc_u32 s51, s49, s41
	global_load_lds_dwordx4 v179, s[50:51]
	v_mfma_f32_16x16x32_bf16 v[12:15], v[170:173], v[206:209], v[12:15]
	v_mfma_f32_16x16x32_bf16 v[8:11], v[170:173], v[210:213], v[8:11]
	s_add_u32 m0, s62, 0xe000
	s_add_u32 s50, s48, s42
	s_addc_u32 s51, s49, s43
	global_load_lds_dwordx4 v179, s[50:51]
	v_mfma_f32_16x16x32_bf16 v[4:7], v[174:177], v[198:201], v[4:7]
	v_mfma_f32_16x16x32_bf16 v[0:3], v[174:177], v[202:205], v[0:3]
	v_mfma_f32_16x16x32_bf16 v[48:51], v[174:177], v[206:209], v[48:51]
	v_mfma_f32_16x16x32_bf16 v[40:43], v[174:177], v[210:213], v[40:43]
	ds_read_b128 v[162:165], v217 offset:8192
	ds_read_b128 v[166:169], v217 offset:10240
	ds_read_b128 v[170:173], v217 offset:12288
	ds_read_b128 v[174:177], v217 offset:14336
	s_waitcnt lgkmcnt(4)
	v_mfma_f32_16x16x32_bf16 v[124:127], v[146:149], v[182:185], v[124:127]
	v_mfma_f32_16x16x32_bf16 v[120:123], v[146:149], v[186:189], v[120:123]
	v_mfma_f32_16x16x32_bf16 v[116:119], v[146:149], v[190:193], v[116:119]
	v_mfma_f32_16x16x32_bf16 v[112:115], v[146:149], v[194:197], v[112:115]
	v_mfma_f32_16x16x32_bf16 v[108:111], v[150:153], v[182:185], v[108:111]
	v_mfma_f32_16x16x32_bf16 v[104:107], v[150:153], v[186:189], v[104:107]
	v_mfma_f32_16x16x32_bf16 v[100:103], v[150:153], v[190:193], v[100:103]
	v_mfma_f32_16x16x32_bf16 v[96:99], v[150:153], v[194:197], v[96:99]
	v_mfma_f32_16x16x32_bf16 v[92:95], v[154:157], v[182:185], v[92:95]
	v_mfma_f32_16x16x32_bf16 v[88:91], v[154:157], v[186:189], v[88:91]
	v_mfma_f32_16x16x32_bf16 v[84:87], v[154:157], v[190:193], v[84:87]
	v_mfma_f32_16x16x32_bf16 v[80:83], v[154:157], v[194:197], v[80:83]
	v_mfma_f32_16x16x32_bf16 v[76:79], v[158:161], v[182:185], v[76:79]
	v_mfma_f32_16x16x32_bf16 v[72:75], v[158:161], v[186:189], v[72:75]
	v_mfma_f32_16x16x32_bf16 v[68:71], v[158:161], v[190:193], v[68:71]
	v_mfma_f32_16x16x32_bf16 v[64:67], v[158:161], v[194:197], v[64:67]
	ds_read_b128 v[146:149], v218
	ds_read_b128 v[150:153], v218 offset:2048
	ds_read_b128 v[154:157], v218 offset:4096
	ds_read_b128 v[158:161], v218 offset:6144
	ds_read_b128 v[198:201], v220 offset:32768
	ds_read_b128 v[202:205], v220 offset:34816
	ds_read_b128 v[206:209], v220 offset:36864
	ds_read_b128 v[210:213], v220 offset:38912
	s_waitcnt lgkmcnt(8)
	v_mfma_f32_16x16x32_bf16 v[60:63], v[162:165], v[182:185], v[60:63]
	v_mfma_f32_16x16x32_bf16 v[56:59], v[162:165], v[186:189], v[56:59]
	v_mfma_f32_16x16x32_bf16 v[52:55], v[162:165], v[190:193], v[52:55]
	v_mfma_f32_16x16x32_bf16 v[44:47], v[162:165], v[194:197], v[44:47]
	v_mfma_f32_16x16x32_bf16 v[36:39], v[166:169], v[182:185], v[36:39]
	v_mfma_f32_16x16x32_bf16 v[32:35], v[166:169], v[186:189], v[32:35]
	v_mfma_f32_16x16x32_bf16 v[28:31], v[166:169], v[190:193], v[28:31]
	v_mfma_f32_16x16x32_bf16 v[24:27], v[166:169], v[194:197], v[24:27]
	v_mfma_f32_16x16x32_bf16 v[20:23], v[170:173], v[182:185], v[20:23]
	v_mfma_f32_16x16x32_bf16 v[16:19], v[170:173], v[186:189], v[16:19]
	v_mfma_f32_16x16x32_bf16 v[12:15], v[170:173], v[190:193], v[12:15]
	v_mfma_f32_16x16x32_bf16 v[8:11], v[170:173], v[194:197], v[8:11]
	v_mfma_f32_16x16x32_bf16 v[4:7], v[174:177], v[182:185], v[4:7]
	v_mfma_f32_16x16x32_bf16 v[0:3], v[174:177], v[186:189], v[0:3]
	v_mfma_f32_16x16x32_bf16 v[48:51], v[174:177], v[190:193], v[48:51]
	v_mfma_f32_16x16x32_bf16 v[40:43], v[174:177], v[194:197], v[40:43]
	ds_read_b128 v[162:165], v218 offset:8192
	ds_read_b128 v[166:169], v218 offset:10240
	ds_read_b128 v[170:173], v218 offset:12288
	ds_read_b128 v[174:177], v218 offset:14336
	s_waitcnt lgkmcnt(4)
	v_mfma_f32_16x16x32_bf16 v[124:127], v[146:149], v[198:201], v[124:127]
	v_mfma_f32_16x16x32_bf16 v[120:123], v[146:149], v[202:205], v[120:123]
	v_mfma_f32_16x16x32_bf16 v[116:119], v[146:149], v[206:209], v[116:119]
	v_mfma_f32_16x16x32_bf16 v[112:115], v[146:149], v[210:213], v[112:115]
	v_mfma_f32_16x16x32_bf16 v[108:111], v[150:153], v[198:201], v[108:111]
	v_mfma_f32_16x16x32_bf16 v[104:107], v[150:153], v[202:205], v[104:107]
	v_mfma_f32_16x16x32_bf16 v[100:103], v[150:153], v[206:209], v[100:103]
	v_mfma_f32_16x16x32_bf16 v[96:99], v[150:153], v[210:213], v[96:99]
	v_mfma_f32_16x16x32_bf16 v[92:95], v[154:157], v[198:201], v[92:95]
	v_mfma_f32_16x16x32_bf16 v[88:91], v[154:157], v[202:205], v[88:91]
	v_mfma_f32_16x16x32_bf16 v[84:87], v[154:157], v[206:209], v[84:87]
	v_mfma_f32_16x16x32_bf16 v[80:83], v[154:157], v[210:213], v[80:83]
	v_mfma_f32_16x16x32_bf16 v[76:79], v[158:161], v[198:201], v[76:79]
	v_mfma_f32_16x16x32_bf16 v[72:75], v[158:161], v[202:205], v[72:75]
	v_mfma_f32_16x16x32_bf16 v[68:71], v[158:161], v[206:209], v[68:71]
	v_mfma_f32_16x16x32_bf16 v[64:67], v[158:161], v[210:213], v[64:67]
	s_add_u32 s48, s48, 0x80
	s_addc_u32 s49, s49, 0
	s_add_i32 s47, s47, 1
	s_branch .Lg2_top

.Lg5_top:
	s_waitcnt lgkmcnt(0)
	s_waitcnt vmcnt(0)
	s_barrier
	s_xor_b32 s87, s87, 0x10000
	s_mov_b32 m0, s87
	s_add_u32 s70, s68, 0x4000080
	s_addc_u32 s71, s69, 0
	global_load_lds_dwordx4 v242, s[70:71]
	s_add_u32 m0, s87, 0x2000
	s_add_u32 s70, s68, 0x4020080
	s_addc_u32 s71, s69, 0
	global_load_lds_dwordx4 v242, s[70:71]
	ds_read_b128 v[176:179], v180
	ds_read_b128 v[182:185], v180 offset:2048
	ds_read_b128 v[186:189], v180 offset:4096
	ds_read_b128 v[190:193], v180 offset:6144
	ds_read_b128 v[210:213], v245 offset:32768
	ds_read_b128 v[214:217], v245 offset:34816
	ds_read_b128 v[218:221], v245 offset:36864
	ds_read_b128 v[222:225], v245 offset:38912
	v_mfma_f32_16x16x32_bf16 v[60:63], v[194:197], v[226:229], v[60:63]
	v_mfma_f32_16x16x32_bf16 v[56:59], v[194:197], v[230:233], v[56:59]
	s_add_u32 m0, s87, 0x4000
	s_add_u32 s70, s68, 0x4040080
	s_addc_u32 s71, s69, 0
	global_load_lds_dwordx4 v242, s[70:71]
	v_mfma_f32_16x16x32_bf16 v[52:55], v[194:197], v[234:237], v[52:55]
	v_mfma_f32_16x16x32_bf16 v[48:51], v[194:197], v[238:241], v[48:51]
	s_add_u32 m0, s87, 0x6000
	s_add_u32 s70, s68, s14
	s_addc_u32 s71, s69, s15
	global_load_lds_dwordx4 v242, s[70:71]
	v_mfma_f32_16x16x32_bf16 v[44:47], v[198:201], v[226:229], v[44:47]
	v_mfma_f32_16x16x32_bf16 v[40:43], v[198:201], v[230:233], v[40:43]
	s_add_u32 m0, s87, 0x8000
	s_add_u32 s70, s68, s16
	s_addc_u32 s71, s69, s17
	global_load_lds_dwordx4 v243, s[70:71]
	v_mfma_f32_16x16x32_bf16 v[36:39], v[198:201], v[234:237], v[36:39]
	v_mfma_f32_16x16x32_bf16 v[32:35], v[198:201], v[238:241], v[32:35]
	s_add_u32 m0, s87, 0xa000
	s_add_u32 s70, s68, s18
	s_addc_u32 s71, s69, s19
	global_load_lds_dwordx4 v243, s[70:71]
	v_mfma_f32_16x16x32_bf16 v[28:31], v[202:205], v[226:229], v[28:31]
	v_mfma_f32_16x16x32_bf16 v[24:27], v[202:205], v[230:233], v[24:27]
	s_add_u32 m0, s87, 0xc000
	s_add_u32 s70, s68, s22
	s_addc_u32 s71, s69, s23
	global_load_lds_dwordx4 v243, s[70:71]
	v_mfma_f32_16x16x32_bf16 v[20:23], v[202:205], v[234:237], v[20:23]
	v_mfma_f32_16x16x32_bf16 v[16:19], v[202:205], v[238:241], v[16:19]
	s_add_u32 m0, s87, 0xe000
	s_add_u32 s70, s68, s36
	s_addc_u32 s71, s69, s37
	global_load_lds_dwordx4 v243, s[70:71]
	v_mfma_f32_16x16x32_bf16 v[8:11], v[206:209], v[226:229], v[8:11]
	v_mfma_f32_16x16x32_bf16 v[0:3], v[206:209], v[230:233], v[0:3]
	v_mfma_f32_16x16x32_bf16 v[12:15], v[206:209], v[234:237], v[12:15]
	v_mfma_f32_16x16x32_bf16 v[4:7], v[206:209], v[238:241], v[4:7]
.Lg5_entry:
	ds_read_b128 v[194:197], v180 offset:8192
	ds_read_b128 v[198:201], v180 offset:10240
	ds_read_b128 v[202:205], v180 offset:12288
	ds_read_b128 v[206:209], v180 offset:14336
	s_waitcnt lgkmcnt(4)
	v_mfma_f32_16x16x32_bf16 v[124:127], v[176:179], v[210:213], v[124:127]
	v_mfma_f32_16x16x32_bf16 v[120:123], v[176:179], v[214:217], v[120:123]
	v_mfma_f32_16x16x32_bf16 v[116:119], v[176:179], v[218:221], v[116:119]
	v_mfma_f32_16x16x32_bf16 v[112:115], v[176:179], v[222:225], v[112:115]
	v_mfma_f32_16x16x32_bf16 v[108:111], v[182:185], v[210:213], v[108:111]
	v_mfma_f32_16x16x32_bf16 v[104:107], v[182:185], v[214:217], v[104:107]
	v_mfma_f32_16x16x32_bf16 v[100:103], v[182:185], v[218:221], v[100:103]
	v_mfma_f32_16x16x32_bf16 v[96:99], v[182:185], v[222:225], v[96:99]
	v_mfma_f32_16x16x32_bf16 v[92:95], v[186:189], v[210:213], v[92:95]
	v_mfma_f32_16x16x32_bf16 v[88:91], v[186:189], v[214:217], v[88:91]
	v_mfma_f32_16x16x32_bf16 v[84:87], v[186:189], v[218:221], v[84:87]
	v_mfma_f32_16x16x32_bf16 v[80:83], v[186:189], v[222:225], v[80:83]
	v_mfma_f32_16x16x32_bf16 v[76:79], v[190:193], v[210:213], v[76:79]
	v_mfma_f32_16x16x32_bf16 v[72:75], v[190:193], v[214:217], v[72:75]
	v_mfma_f32_16x16x32_bf16 v[68:71], v[190:193], v[218:221], v[68:71]
	v_mfma_f32_16x16x32_bf16 v[64:67], v[190:193], v[222:225], v[64:67]
	ds_read_b128 v[176:179], v244
	ds_read_b128 v[182:185], v244 offset:2048
	ds_read_b128 v[186:189], v244 offset:4096
	ds_read_b128 v[190:193], v244 offset:6144
	ds_read_b128 v[226:229], v246 offset:32768
	ds_read_b128 v[230:233], v246 offset:34816
	ds_read_b128 v[234:237], v246 offset:36864
	ds_read_b128 v[238:241], v246 offset:38912
	s_waitcnt lgkmcnt(8)
	v_mfma_f32_16x16x32_bf16 v[60:63], v[194:197], v[210:213], v[60:63]
	v_mfma_f32_16x16x32_bf16 v[56:59], v[194:197], v[214:217], v[56:59]
	v_mfma_f32_16x16x32_bf16 v[52:55], v[194:197], v[218:221], v[52:55]
	v_mfma_f32_16x16x32_bf16 v[48:51], v[194:197], v[222:225], v[48:51]
	v_mfma_f32_16x16x32_bf16 v[44:47], v[198:201], v[210:213], v[44:47]
	v_mfma_f32_16x16x32_bf16 v[40:43], v[198:201], v[214:217], v[40:43]
	v_mfma_f32_16x16x32_bf16 v[36:39], v[198:201], v[218:221], v[36:39]
	v_mfma_f32_16x16x32_bf16 v[32:35], v[198:201], v[222:225], v[32:35]
	v_mfma_f32_16x16x32_bf16 v[28:31], v[202:205], v[210:213], v[28:31]
	v_mfma_f32_16x16x32_bf16 v[24:27], v[202:205], v[214:217], v[24:27]
	v_mfma_f32_16x16x32_bf16 v[20:23], v[202:205], v[218:221], v[20:23]
	v_mfma_f32_16x16x32_bf16 v[16:19], v[202:205], v[222:225], v[16:19]
	v_mfma_f32_16x16x32_bf16 v[8:11], v[206:209], v[210:213], v[8:11]
	v_mfma_f32_16x16x32_bf16 v[0:3], v[206:209], v[214:217], v[0:3]
	v_mfma_f32_16x16x32_bf16 v[12:15], v[206:209], v[218:221], v[12:15]
	v_mfma_f32_16x16x32_bf16 v[4:7], v[206:209], v[222:225], v[4:7]
	ds_read_b128 v[194:197], v244 offset:8192
	ds_read_b128 v[198:201], v244 offset:10240
	ds_read_b128 v[202:205], v244 offset:12288
	ds_read_b128 v[206:209], v244 offset:14336
	s_waitcnt lgkmcnt(4)
	v_mfma_f32_16x16x32_bf16 v[124:127], v[176:179], v[226:229], v[124:127]
	v_mfma_f32_16x16x32_bf16 v[120:123], v[176:179], v[230:233], v[120:123]
	v_mfma_f32_16x16x32_bf16 v[116:119], v[176:179], v[234:237], v[116:119]
	v_mfma_f32_16x16x32_bf16 v[112:115], v[176:179], v[238:241], v[112:115]
	v_mfma_f32_16x16x32_bf16 v[108:111], v[182:185], v[226:229], v[108:111]
	v_mfma_f32_16x16x32_bf16 v[104:107], v[182:185], v[230:233], v[104:107]
	v_mfma_f32_16x16x32_bf16 v[100:103], v[182:185], v[234:237], v[100:103]
	v_mfma_f32_16x16x32_bf16 v[96:99], v[182:185], v[238:241], v[96:99]
	v_mfma_f32_16x16x32_bf16 v[92:95], v[186:189], v[226:229], v[92:95]
	v_mfma_f32_16x16x32_bf16 v[88:91], v[186:189], v[230:233], v[88:91]
	v_mfma_f32_16x16x32_bf16 v[84:87], v[186:189], v[234:237], v[84:87]
	v_mfma_f32_16x16x32_bf16 v[80:83], v[186:189], v[238:241], v[80:83]
	v_mfma_f32_16x16x32_bf16 v[76:79], v[190:193], v[226:229], v[76:79]
	v_mfma_f32_16x16x32_bf16 v[72:75], v[190:193], v[230:233], v[72:75]
	v_mfma_f32_16x16x32_bf16 v[68:71], v[190:193], v[234:237], v[68:71]
	v_mfma_f32_16x16x32_bf16 v[64:67], v[190:193], v[238:241], v[64:67]
	s_add_u32 s68, s68, 0x80
	s_addc_u32 s69, s69, 0
	s_add_i32 s86, s86, 1
	s_cmp_lt_u32 s86, 15
	s_cbranch_scc0 .Lg5_last
	s_waitcnt lgkmcnt(0)
	s_waitcnt vmcnt(0)
	s_barrier
	s_xor_b32 s87, s87, 0x10000
	s_mov_b32 m0, s87
	s_add_u32 s70, s68, 0x4000080
	s_addc_u32 s71, s69, 0
	global_load_lds_dwordx4 v242, s[70:71]
	s_add_u32 m0, s87, 0x2000
	s_add_u32 s70, s68, 0x4020080
	s_addc_u32 s71, s69, 0
	global_load_lds_dwordx4 v242, s[70:71]
	ds_read_b128 v[176:179], v247
	ds_read_b128 v[182:185], v247 offset:2048
	ds_read_b128 v[186:189], v247 offset:4096
	ds_read_b128 v[190:193], v247 offset:6144
	ds_read_b128 v[210:213], v249 offset:32768
	ds_read_b128 v[214:217], v249 offset:34816
	ds_read_b128 v[218:221], v249 offset:36864
	ds_read_b128 v[222:225], v249 offset:38912
	v_mfma_f32_16x16x32_bf16 v[60:63], v[194:197], v[226:229], v[60:63]
	v_mfma_f32_16x16x32_bf16 v[56:59], v[194:197], v[230:233], v[56:59]
	s_add_u32 m0, s87, 0x4000
	s_add_u32 s70, s68, 0x4040080
	s_addc_u32 s71, s69, 0
	global_load_lds_dwordx4 v242, s[70:71]
	v_mfma_f32_16x16x32_bf16 v[52:55], v[194:197], v[234:237], v[52:55]
	v_mfma_f32_16x16x32_bf16 v[48:51], v[194:197], v[238:241], v[48:51]
	s_add_u32 m0, s87, 0x6000
	s_add_u32 s70, s68, s14
	s_addc_u32 s71, s69, s15
	global_load_lds_dwordx4 v242, s[70:71]
	v_mfma_f32_16x16x32_bf16 v[44:47], v[198:201], v[226:229], v[44:47]
	v_mfma_f32_16x16x32_bf16 v[40:43], v[198:201], v[230:233], v[40:43]
	s_add_u32 m0, s87, 0x8000
	s_add_u32 s70, s68, s16
	s_addc_u32 s71, s69, s17
	global_load_lds_dwordx4 v243, s[70:71]
	v_mfma_f32_16x16x32_bf16 v[36:39], v[198:201], v[234:237], v[36:39]
	v_mfma_f32_16x16x32_bf16 v[32:35], v[198:201], v[238:241], v[32:35]
	s_add_u32 m0, s87, 0xa000
	s_add_u32 s70, s68, s18
	s_addc_u32 s71, s69, s19
	global_load_lds_dwordx4 v243, s[70:71]
	v_mfma_f32_16x16x32_bf16 v[28:31], v[202:205], v[226:229], v[28:31]
	v_mfma_f32_16x16x32_bf16 v[24:27], v[202:205], v[230:233], v[24:27]
	s_add_u32 m0, s87, 0xc000
	s_add_u32 s70, s68, s22
	s_addc_u32 s71, s69, s23
	global_load_lds_dwordx4 v243, s[70:71]
	v_mfma_f32_16x16x32_bf16 v[20:23], v[202:205], v[234:237], v[20:23]
	v_mfma_f32_16x16x32_bf16 v[16:19], v[202:205], v[238:241], v[16:19]
	s_add_u32 m0, s87, 0xe000
	s_add_u32 s70, s68, s36
	s_addc_u32 s71, s69, s37
	global_load_lds_dwordx4 v243, s[70:71]
	v_mfma_f32_16x16x32_bf16 v[8:11], v[206:209], v[226:229], v[8:11]
	v_mfma_f32_16x16x32_bf16 v[0:3], v[206:209], v[230:233], v[0:3]
	v_mfma_f32_16x16x32_bf16 v[12:15], v[206:209], v[234:237], v[12:15]
	v_mfma_f32_16x16x32_bf16 v[4:7], v[206:209], v[238:241], v[4:7]
	ds_read_b128 v[194:197], v247 offset:8192
	ds_read_b128 v[198:201], v247 offset:10240
	ds_read_b128 v[202:205], v247 offset:12288
	ds_read_b128 v[206:209], v247 offset:14336
	s_waitcnt lgkmcnt(4)
	v_mfma_f32_16x16x32_bf16 v[124:127], v[176:179], v[210:213], v[124:127]
	v_mfma_f32_16x16x32_bf16 v[120:123], v[176:179], v[214:217], v[120:123]
	v_mfma_f32_16x16x32_bf16 v[116:119], v[176:179], v[218:221], v[116:119]
	v_mfma_f32_16x16x32_bf16 v[112:115], v[176:179], v[222:225], v[112:115]
	v_mfma_f32_16x16x32_bf16 v[108:111], v[182:185], v[210:213], v[108:111]
	v_mfma_f32_16x16x32_bf16 v[104:107], v[182:185], v[214:217], v[104:107]
	v_mfma_f32_16x16x32_bf16 v[100:103], v[182:185], v[218:221], v[100:103]
	v_mfma_f32_16x16x32_bf16 v[96:99], v[182:185], v[222:225], v[96:99]
	v_mfma_f32_16x16x32_bf16 v[92:95], v[186:189], v[210:213], v[92:95]
	v_mfma_f32_16x16x32_bf16 v[88:91], v[186:189], v[214:217], v[88:91]
	v_mfma_f32_16x16x32_bf16 v[84:87], v[186:189], v[218:221], v[84:87]
	v_mfma_f32_16x16x32_bf16 v[80:83], v[186:189], v[222:225], v[80:83]
	v_mfma_f32_16x16x32_bf16 v[76:79], v[190:193], v[210:213], v[76:79]
	v_mfma_f32_16x16x32_bf16 v[72:75], v[190:193], v[214:217], v[72:75]
	v_mfma_f32_16x16x32_bf16 v[68:71], v[190:193], v[218:221], v[68:71]
	v_mfma_f32_16x16x32_bf16 v[64:67], v[190:193], v[222:225], v[64:67]
	ds_read_b128 v[176:179], v248
	ds_read_b128 v[182:185], v248 offset:2048
	ds_read_b128 v[186:189], v248 offset:4096
	ds_read_b128 v[190:193], v248 offset:6144
	ds_read_b128 v[226:229], v250 offset:32768
	ds_read_b128 v[230:233], v250 offset:34816
	ds_read_b128 v[234:237], v250 offset:36864
	ds_read_b128 v[238:241], v250 offset:38912
	s_waitcnt lgkmcnt(8)
	v_mfma_f32_16x16x32_bf16 v[60:63], v[194:197], v[210:213], v[60:63]
	v_mfma_f32_16x16x32_bf16 v[56:59], v[194:197], v[214:217], v[56:59]
	v_mfma_f32_16x16x32_bf16 v[52:55], v[194:197], v[218:221], v[52:55]
	v_mfma_f32_16x16x32_bf16 v[48:51], v[194:197], v[222:225], v[48:51]
	v_mfma_f32_16x16x32_bf16 v[44:47], v[198:201], v[210:213], v[44:47]
	v_mfma_f32_16x16x32_bf16 v[40:43], v[198:201], v[214:217], v[40:43]
	v_mfma_f32_16x16x32_bf16 v[36:39], v[198:201], v[218:221], v[36:39]
	v_mfma_f32_16x16x32_bf16 v[32:35], v[198:201], v[222:225], v[32:35]
	v_mfma_f32_16x16x32_bf16 v[28:31], v[202:205], v[210:213], v[28:31]
	v_mfma_f32_16x16x32_bf16 v[24:27], v[202:205], v[214:217], v[24:27]
	v_mfma_f32_16x16x32_bf16 v[20:23], v[202:205], v[218:221], v[20:23]
	v_mfma_f32_16x16x32_bf16 v[16:19], v[202:205], v[222:225], v[16:19]
	v_mfma_f32_16x16x32_bf16 v[8:11], v[206:209], v[210:213], v[8:11]
	v_mfma_f32_16x16x32_bf16 v[0:3], v[206:209], v[214:217], v[0:3]
	v_mfma_f32_16x16x32_bf16 v[12:15], v[206:209], v[218:221], v[12:15]
	v_mfma_f32_16x16x32_bf16 v[4:7], v[206:209], v[222:225], v[4:7]
	ds_read_b128 v[194:197], v248 offset:8192
	ds_read_b128 v[198:201], v248 offset:10240
	ds_read_b128 v[202:205], v248 offset:12288
	ds_read_b128 v[206:209], v248 offset:14336
	s_waitcnt lgkmcnt(4)
	v_mfma_f32_16x16x32_bf16 v[124:127], v[176:179], v[226:229], v[124:127]
	v_mfma_f32_16x16x32_bf16 v[120:123], v[176:179], v[230:233], v[120:123]
	v_mfma_f32_16x16x32_bf16 v[116:119], v[176:179], v[234:237], v[116:119]
	v_mfma_f32_16x16x32_bf16 v[112:115], v[176:179], v[238:241], v[112:115]
	v_mfma_f32_16x16x32_bf16 v[108:111], v[182:185], v[226:229], v[108:111]
	v_mfma_f32_16x16x32_bf16 v[104:107], v[182:185], v[230:233], v[104:107]
	v_mfma_f32_16x16x32_bf16 v[100:103], v[182:185], v[234:237], v[100:103]
	v_mfma_f32_16x16x32_bf16 v[96:99], v[182:185], v[238:241], v[96:99]
	v_mfma_f32_16x16x32_bf16 v[92:95], v[186:189], v[226:229], v[92:95]
	v_mfma_f32_16x16x32_bf16 v[88:91], v[186:189], v[230:233], v[88:91]
	v_mfma_f32_16x16x32_bf16 v[84:87], v[186:189], v[234:237], v[84:87]
	v_mfma_f32_16x16x32_bf16 v[80:83], v[186:189], v[238:241], v[80:83]
	v_mfma_f32_16x16x32_bf16 v[76:79], v[190:193], v[226:229], v[76:79]
	v_mfma_f32_16x16x32_bf16 v[72:75], v[190:193], v[230:233], v[72:75]
	v_mfma_f32_16x16x32_bf16 v[68:71], v[190:193], v[234:237], v[68:71]
	v_mfma_f32_16x16x32_bf16 v[64:67], v[190:193], v[238:241], v[64:67]
	s_add_u32 s68, s68, 0x80
	s_addc_u32 s69, s69, 0
	s_add_i32 s86, s86, 1
	s_branch .Lg5_top

.Lg6_top:
	s_waitcnt lgkmcnt(0)
	s_waitcnt vmcnt(0)
	s_barrier
	v_xor_b32_e32 v180, 0x10000, v180
	v_xor_b32_e32 v249, 0x10000, v249
	v_xor_b32_e32 v248, 0x10000, v248
	v_xor_b32_e32 v250, 0x10000, v250
	s_xor_b32 s69, s69, 0x10000
	s_mov_b32 m0, s69
	s_add_u32 s66, s64, s44
	s_addc_u32 s67, s65, s45
	global_load_lds_dwordx4 v246, s[66:67]
	s_add_u32 m0, s69, 0x2000
	s_add_u32 s66, s64, s46
	s_addc_u32 s67, s65, s47
	global_load_lds_dwordx4 v246, s[66:67]
	ds_read_b128 v[182:185], v180
	ds_read_b128 v[186:189], v180 offset:2048
	ds_read_b128 v[190:193], v180 offset:4096
	ds_read_b128 v[194:197], v180 offset:6144
	ds_read_b128 v[214:217], v249 offset:32768
	ds_read_b128 v[218:221], v249 offset:34816
	ds_read_b128 v[222:225], v249 offset:36864
	ds_read_b128 v[226:229], v249 offset:38912
	v_mfma_f32_16x16x32_bf16 v[60:63], v[198:201], v[230:233], v[60:63]
	v_mfma_f32_16x16x32_bf16 v[56:59], v[198:201], v[234:237], v[56:59]
	s_add_u32 m0, s69, 0x4000
	s_add_u32 s66, s64, s48
	s_addc_u32 s67, s65, s49
	global_load_lds_dwordx4 v246, s[66:67]
	v_mfma_f32_16x16x32_bf16 v[52:55], v[198:201], v[238:241], v[52:55]
	v_mfma_f32_16x16x32_bf16 v[48:51], v[198:201], v[242:245], v[48:51]
	s_add_u32 m0, s69, 0x6000
	s_add_u32 s66, s64, s50
	s_addc_u32 s67, s65, s51
	global_load_lds_dwordx4 v246, s[66:67]
	v_mfma_f32_16x16x32_bf16 v[44:47], v[202:205], v[230:233], v[44:47]
	v_mfma_f32_16x16x32_bf16 v[40:43], v[202:205], v[234:237], v[40:43]
	s_add_u32 m0, s69, 0x8000
	s_add_u32 s66, s64, s52
	s_addc_u32 s67, s65, s53
	global_load_lds_dwordx4 v247, s[66:67]
	v_mfma_f32_16x16x32_bf16 v[36:39], v[202:205], v[238:241], v[36:39]
	v_mfma_f32_16x16x32_bf16 v[32:35], v[202:205], v[242:245], v[32:35]
	s_add_u32 m0, s69, 0xa000
	s_add_u32 s66, s64, s54
	s_addc_u32 s67, s65, s55
	global_load_lds_dwordx4 v247, s[66:67]
	v_mfma_f32_16x16x32_bf16 v[28:31], v[206:209], v[230:233], v[28:31]
	v_mfma_f32_16x16x32_bf16 v[24:27], v[206:209], v[234:237], v[24:27]
	s_add_u32 m0, s69, 0xc000
	s_add_u32 s66, s64, s60
	s_addc_u32 s67, s65, s61
	global_load_lds_dwordx4 v247, s[66:67]
	v_mfma_f32_16x16x32_bf16 v[20:23], v[206:209], v[238:241], v[20:23]
	v_mfma_f32_16x16x32_bf16 v[16:19], v[206:209], v[242:245], v[16:19]
	s_add_u32 m0, s69, 0xe000
	s_add_u32 s66, s64, s62
	s_addc_u32 s67, s65, s63
	global_load_lds_dwordx4 v247, s[66:67]
	v_mfma_f32_16x16x32_bf16 v[12:15], v[210:213], v[230:233], v[12:15]
	v_mfma_f32_16x16x32_bf16 v[0:3], v[210:213], v[234:237], v[0:3]
	v_mfma_f32_16x16x32_bf16 v[8:11], v[210:213], v[238:241], v[8:11]
	v_mfma_f32_16x16x32_bf16 v[4:7], v[210:213], v[242:245], v[4:7]

.Lg7_top:
	s_waitcnt lgkmcnt(0)
	s_waitcnt vmcnt(0)
	s_barrier
	s_xor_b32 s61, s61, 0x10000
	s_mov_b32 m0, s61
	s_add_u32 s50, s48, s14
	s_addc_u32 s51, s49, s15
	global_load_lds_dwordx4 v178, s[50:51]
	s_add_u32 m0, s61, 0x2000
	s_add_u32 s50, s48, s16
	s_addc_u32 s51, s49, s17
	global_load_lds_dwordx4 v178, s[50:51]
	ds_read_b128 v[142:145], v141
	ds_read_b128 v[146:149], v141 offset:2048
	ds_read_b128 v[150:153], v141 offset:4096
	ds_read_b128 v[154:157], v141 offset:6144
	ds_read_b128 v[174:177], v210 offset:32768
	ds_read_b128 v[182:185], v210 offset:34816
	ds_read_b128 v[186:189], v210 offset:36864
	ds_read_b128 v[190:193], v210 offset:38912
	v_mfma_f32_16x16x32_bf16 v[60:63], v[158:161], v[194:197], v[60:63]
	v_mfma_f32_16x16x32_bf16 v[56:59], v[158:161], v[198:201], v[56:59]
	s_add_u32 m0, s61, 0x4000
	s_add_u32 s50, s48, s18
	s_addc_u32 s51, s49, s19
	global_load_lds_dwordx4 v178, s[50:51]
	v_mfma_f32_16x16x32_bf16 v[52:55], v[158:161], v[202:205], v[52:55]
	v_mfma_f32_16x16x32_bf16 v[48:51], v[158:161], v[206:209], v[48:51]
	s_add_u32 m0, s61, 0x6000
	s_add_u32 s50, s48, s22
	s_addc_u32 s51, s49, s23
	global_load_lds_dwordx4 v178, s[50:51]
	v_mfma_f32_16x16x32_bf16 v[44:47], v[162:165], v[194:197], v[44:47]
	v_mfma_f32_16x16x32_bf16 v[32:35], v[162:165], v[198:201], v[32:35]
	s_add_u32 m0, s61, 0x8000
	s_add_u32 s50, s48, s36
	s_addc_u32 s51, s49, s37
	global_load_lds_dwordx4 v179, s[50:51]
	v_mfma_f32_16x16x32_bf16 v[28:31], v[162:165], v[202:205], v[28:31]
	v_mfma_f32_16x16x32_bf16 v[24:27], v[162:165], v[206:209], v[24:27]
	s_add_u32 m0, s61, 0xa000
	s_add_u32 s50, s48, s40
	s_addc_u32 s51, s49, s41
	global_load_lds_dwordx4 v179, s[50:51]
	v_mfma_f32_16x16x32_bf16 v[20:23], v[166:169], v[194:197], v[20:23]
	v_mfma_f32_16x16x32_bf16 v[16:19], v[166:169], v[198:201], v[16:19]
	s_add_u32 m0, s61, 0xc000
	s_add_u32 s50, s48, s42
	s_addc_u32 s51, s49, s43
	global_load_lds_dwordx4 v179, s[50:51]
	v_mfma_f32_16x16x32_bf16 v[12:15], v[166:169], v[202:205], v[12:15]
	v_mfma_f32_16x16x32_bf16 v[8:11], v[166:169], v[206:209], v[8:11]
	s_add_u32 m0, s61, 0xe000
	s_add_u32 s50, s48, s44
	s_addc_u32 s51, s49, s45
	global_load_lds_dwordx4 v179, s[50:51]
	v_mfma_f32_16x16x32_bf16 v[4:7], v[170:173], v[194:197], v[4:7]
	v_mfma_f32_16x16x32_bf16 v[0:3], v[170:173], v[198:201], v[0:3]
	v_mfma_f32_16x16x32_bf16 v[40:43], v[170:173], v[202:205], v[40:43]
	v_mfma_f32_16x16x32_bf16 v[36:39], v[170:173], v[206:209], v[36:39]
.Lg7_entry:
	ds_read_b128 v[158:161], v141 offset:8192
	ds_read_b128 v[162:165], v141 offset:10240
	ds_read_b128 v[166:169], v141 offset:12288
	ds_read_b128 v[170:173], v141 offset:14336
	s_waitcnt lgkmcnt(4)
	v_mfma_f32_16x16x32_bf16 v[124:127], v[142:145], v[174:177], v[124:127]
	v_mfma_f32_16x16x32_bf16 v[120:123], v[142:145], v[182:185], v[120:123]
	v_mfma_f32_16x16x32_bf16 v[116:119], v[142:145], v[186:189], v[116:119]
	v_mfma_f32_16x16x32_bf16 v[112:115], v[142:145], v[190:193], v[112:115]
	v_mfma_f32_16x16x32_bf16 v[108:111], v[146:149], v[174:177], v[108:111]
	v_mfma_f32_16x16x32_bf16 v[104:107], v[146:149], v[182:185], v[104:107]
	v_mfma_f32_16x16x32_bf16 v[100:103], v[146:149], v[186:189], v[100:103]
	v_mfma_f32_16x16x32_bf16 v[96:99], v[146:149], v[190:193], v[96:99]
	v_mfma_f32_16x16x32_bf16 v[92:95], v[150:153], v[174:177], v[92:95]
	v_mfma_f32_16x16x32_bf16 v[88:91], v[150:153], v[182:185], v[88:91]
	v_mfma_f32_16x16x32_bf16 v[84:87], v[150:153], v[186:189], v[84:87]
	v_mfma_f32_16x16x32_bf16 v[80:83], v[150:153], v[190:193], v[80:83]
	v_mfma_f32_16x16x32_bf16 v[76:79], v[154:157], v[174:177], v[76:79]
	v_mfma_f32_16x16x32_bf16 v[72:75], v[154:157], v[182:185], v[72:75]
	v_mfma_f32_16x16x32_bf16 v[68:71], v[154:157], v[186:189], v[68:71]
	v_mfma_f32_16x16x32_bf16 v[64:67], v[154:157], v[190:193], v[64:67]
	ds_read_b128 v[142:145], v180
	ds_read_b128 v[146:149], v180 offset:2048
	ds_read_b128 v[150:153], v180 offset:4096
	ds_read_b128 v[154:157], v180 offset:6144
	ds_read_b128 v[194:197], v211 offset:32768
	ds_read_b128 v[198:201], v211 offset:34816
	ds_read_b128 v[202:205], v211 offset:36864
	ds_read_b128 v[206:209], v211 offset:38912
	s_waitcnt lgkmcnt(8)
	v_mfma_f32_16x16x32_bf16 v[60:63], v[158:161], v[174:177], v[60:63]
	v_mfma_f32_16x16x32_bf16 v[56:59], v[158:161], v[182:185], v[56:59]
	v_mfma_f32_16x16x32_bf16 v[52:55], v[158:161], v[186:189], v[52:55]
	v_mfma_f32_16x16x32_bf16 v[48:51], v[158:161], v[190:193], v[48:51]
	v_mfma_f32_16x16x32_bf16 v[44:47], v[162:165], v[174:177], v[44:47]
	v_mfma_f32_16x16x32_bf16 v[32:35], v[162:165], v[182:185], v[32:35]
	v_mfma_f32_16x16x32_bf16 v[28:31], v[162:165], v[186:189], v[28:31]
	v_mfma_f32_16x16x32_bf16 v[24:27], v[162:165], v[190:193], v[24:27]
	v_mfma_f32_16x16x32_bf16 v[20:23], v[166:169], v[174:177], v[20:23]
	v_mfma_f32_16x16x32_bf16 v[16:19], v[166:169], v[182:185], v[16:19]
	v_mfma_f32_16x16x32_bf16 v[12:15], v[166:169], v[186:189], v[12:15]
	v_mfma_f32_16x16x32_bf16 v[8:11], v[166:169], v[190:193], v[8:11]
	v_mfma_f32_16x16x32_bf16 v[4:7], v[170:173], v[174:177], v[4:7]
	v_mfma_f32_16x16x32_bf16 v[0:3], v[170:173], v[182:185], v[0:3]
	v_mfma_f32_16x16x32_bf16 v[40:43], v[170:173], v[186:189], v[40:43]
	v_mfma_f32_16x16x32_bf16 v[36:39], v[170:173], v[190:193], v[36:39]
	ds_read_b128 v[158:161], v180 offset:8192
	ds_read_b128 v[162:165], v180 offset:10240
	ds_read_b128 v[166:169], v180 offset:12288
	ds_read_b128 v[170:173], v180 offset:14336
	s_waitcnt lgkmcnt(4)
	v_mfma_f32_16x16x32_bf16 v[124:127], v[142:145], v[194:197], v[124:127]
	v_mfma_f32_16x16x32_bf16 v[120:123], v[142:145], v[198:201], v[120:123]
	v_mfma_f32_16x16x32_bf16 v[116:119], v[142:145], v[202:205], v[116:119]
	v_mfma_f32_16x16x32_bf16 v[112:115], v[142:145], v[206:209], v[112:115]
	v_mfma_f32_16x16x32_bf16 v[108:111], v[146:149], v[194:197], v[108:111]
	v_mfma_f32_16x16x32_bf16 v[104:107], v[146:149], v[198:201], v[104:107]
	v_mfma_f32_16x16x32_bf16 v[100:103], v[146:149], v[202:205], v[100:103]
	v_mfma_f32_16x16x32_bf16 v[96:99], v[146:149], v[206:209], v[96:99]
	v_mfma_f32_16x16x32_bf16 v[92:95], v[150:153], v[194:197], v[92:95]
	v_mfma_f32_16x16x32_bf16 v[88:91], v[150:153], v[198:201], v[88:91]
	v_mfma_f32_16x16x32_bf16 v[84:87], v[150:153], v[202:205], v[84:87]
	v_mfma_f32_16x16x32_bf16 v[80:83], v[150:153], v[206:209], v[80:83]
	v_mfma_f32_16x16x32_bf16 v[76:79], v[154:157], v[194:197], v[76:79]
	v_mfma_f32_16x16x32_bf16 v[72:75], v[154:157], v[198:201], v[72:75]
	v_mfma_f32_16x16x32_bf16 v[68:71], v[154:157], v[202:205], v[68:71]
	v_mfma_f32_16x16x32_bf16 v[64:67], v[154:157], v[206:209], v[64:67]
	s_add_u32 s48, s48, 0x80
	s_addc_u32 s49, s49, 0
	s_add_i32 s47, s47, 1
	s_cmp_lt_u32 s47, 31
	s_cbranch_scc0 .Lg7_last
	s_waitcnt lgkmcnt(0)
	s_waitcnt vmcnt(0)
	s_barrier
	s_xor_b32 s61, s61, 0x10000
	s_mov_b32 m0, s61
	s_add_u32 s50, s48, s14
	s_addc_u32 s51, s49, s15
	global_load_lds_dwordx4 v178, s[50:51]
	s_add_u32 m0, s61, 0x2000
	s_add_u32 s50, s48, s16
	s_addc_u32 s51, s49, s17
	global_load_lds_dwordx4 v178, s[50:51]
	ds_read_b128 v[142:145], v212
	ds_read_b128 v[146:149], v212 offset:2048
	ds_read_b128 v[150:153], v212 offset:4096
	ds_read_b128 v[154:157], v212 offset:6144
	ds_read_b128 v[174:177], v214 offset:32768
	ds_read_b128 v[182:185], v214 offset:34816
	ds_read_b128 v[186:189], v214 offset:36864
	ds_read_b128 v[190:193], v214 offset:38912
	v_mfma_f32_16x16x32_bf16 v[60:63], v[158:161], v[194:197], v[60:63]
	v_mfma_f32_16x16x32_bf16 v[56:59], v[158:161], v[198:201], v[56:59]
	s_add_u32 m0, s61, 0x4000
	s_add_u32 s50, s48, s18
	s_addc_u32 s51, s49, s19
	global_load_lds_dwordx4 v178, s[50:51]
	v_mfma_f32_16x16x32_bf16 v[52:55], v[158:161], v[202:205], v[52:55]
	v_mfma_f32_16x16x32_bf16 v[48:51], v[158:161], v[206:209], v[48:51]
	s_add_u32 m0, s61, 0x6000
	s_add_u32 s50, s48, s22
	s_addc_u32 s51, s49, s23
	global_load_lds_dwordx4 v178, s[50:51]
	v_mfma_f32_16x16x32_bf16 v[44:47], v[162:165], v[194:197], v[44:47]
	v_mfma_f32_16x16x32_bf16 v[32:35], v[162:165], v[198:201], v[32:35]
	s_add_u32 m0, s61, 0x8000
	s_add_u32 s50, s48, s36
	s_addc_u32 s51, s49, s37
	global_load_lds_dwordx4 v179, s[50:51]
	v_mfma_f32_16x16x32_bf16 v[28:31], v[162:165], v[202:205], v[28:31]
	v_mfma_f32_16x16x32_bf16 v[24:27], v[162:165], v[206:209], v[24:27]
	s_add_u32 m0, s61, 0xa000
	s_add_u32 s50, s48, s40
	s_addc_u32 s51, s49, s41
	global_load_lds_dwordx4 v179, s[50:51]
	v_mfma_f32_16x16x32_bf16 v[20:23], v[166:169], v[194:197], v[20:23]
	v_mfma_f32_16x16x32_bf16 v[16:19], v[166:169], v[198:201], v[16:19]
	s_add_u32 m0, s61, 0xc000
	s_add_u32 s50, s48, s42
	s_addc_u32 s51, s49, s43
	global_load_lds_dwordx4 v179, s[50:51]
	v_mfma_f32_16x16x32_bf16 v[12:15], v[166:169], v[202:205], v[12:15]
	v_mfma_f32_16x16x32_bf16 v[8:11], v[166:169], v[206:209], v[8:11]
	s_add_u32 m0, s61, 0xe000
	s_add_u32 s50, s48, s44
	s_addc_u32 s51, s49, s45
	global_load_lds_dwordx4 v179, s[50:51]
	v_mfma_f32_16x16x32_bf16 v[4:7], v[170:173], v[194:197], v[4:7]
	v_mfma_f32_16x16x32_bf16 v[0:3], v[170:173], v[198:201], v[0:3]
	v_mfma_f32_16x16x32_bf16 v[40:43], v[170:173], v[202:205], v[40:43]
	v_mfma_f32_16x16x32_bf16 v[36:39], v[170:173], v[206:209], v[36:39]
	ds_read_b128 v[158:161], v212 offset:8192
	ds_read_b128 v[162:165], v212 offset:10240
	ds_read_b128 v[166:169], v212 offset:12288
	ds_read_b128 v[170:173], v212 offset:14336
	s_waitcnt lgkmcnt(4)
	v_mfma_f32_16x16x32_bf16 v[124:127], v[142:145], v[174:177], v[124:127]
	v_mfma_f32_16x16x32_bf16 v[120:123], v[142:145], v[182:185], v[120:123]
	v_mfma_f32_16x16x32_bf16 v[116:119], v[142:145], v[186:189], v[116:119]
	v_mfma_f32_16x16x32_bf16 v[112:115], v[142:145], v[190:193], v[112:115]
	v_mfma_f32_16x16x32_bf16 v[108:111], v[146:149], v[174:177], v[108:111]
	v_mfma_f32_16x16x32_bf16 v[104:107], v[146:149], v[182:185], v[104:107]
	v_mfma_f32_16x16x32_bf16 v[100:103], v[146:149], v[186:189], v[100:103]
	v_mfma_f32_16x16x32_bf16 v[96:99], v[146:149], v[190:193], v[96:99]
	v_mfma_f32_16x16x32_bf16 v[92:95], v[150:153], v[174:177], v[92:95]
	v_mfma_f32_16x16x32_bf16 v[88:91], v[150:153], v[182:185], v[88:91]
	v_mfma_f32_16x16x32_bf16 v[84:87], v[150:153], v[186:189], v[84:87]
	v_mfma_f32_16x16x32_bf16 v[80:83], v[150:153], v[190:193], v[80:83]
	v_mfma_f32_16x16x32_bf16 v[76:79], v[154:157], v[174:177], v[76:79]
	v_mfma_f32_16x16x32_bf16 v[72:75], v[154:157], v[182:185], v[72:75]
	v_mfma_f32_16x16x32_bf16 v[68:71], v[154:157], v[186:189], v[68:71]
	v_mfma_f32_16x16x32_bf16 v[64:67], v[154:157], v[190:193], v[64:67]
	ds_read_b128 v[142:145], v213
	ds_read_b128 v[146:149], v213 offset:2048
	ds_read_b128 v[150:153], v213 offset:4096
	ds_read_b128 v[154:157], v213 offset:6144
	ds_read_b128 v[194:197], v215 offset:32768
	ds_read_b128 v[198:201], v215 offset:34816
	ds_read_b128 v[202:205], v215 offset:36864
	ds_read_b128 v[206:209], v215 offset:38912
	s_waitcnt lgkmcnt(8)
	v_mfma_f32_16x16x32_bf16 v[60:63], v[158:161], v[174:177], v[60:63]
	v_mfma_f32_16x16x32_bf16 v[56:59], v[158:161], v[182:185], v[56:59]
	v_mfma_f32_16x16x32_bf16 v[52:55], v[158:161], v[186:189], v[52:55]
	v_mfma_f32_16x16x32_bf16 v[48:51], v[158:161], v[190:193], v[48:51]
	v_mfma_f32_16x16x32_bf16 v[44:47], v[162:165], v[174:177], v[44:47]
	v_mfma_f32_16x16x32_bf16 v[32:35], v[162:165], v[182:185], v[32:35]
	v_mfma_f32_16x16x32_bf16 v[28:31], v[162:165], v[186:189], v[28:31]
	v_mfma_f32_16x16x32_bf16 v[24:27], v[162:165], v[190:193], v[24:27]
	v_mfma_f32_16x16x32_bf16 v[20:23], v[166:169], v[174:177], v[20:23]
	v_mfma_f32_16x16x32_bf16 v[16:19], v[166:169], v[182:185], v[16:19]
	v_mfma_f32_16x16x32_bf16 v[12:15], v[166:169], v[186:189], v[12:15]
	v_mfma_f32_16x16x32_bf16 v[8:11], v[166:169], v[190:193], v[8:11]
	v_mfma_f32_16x16x32_bf16 v[4:7], v[170:173], v[174:177], v[4:7]
	v_mfma_f32_16x16x32_bf16 v[0:3], v[170:173], v[182:185], v[0:3]
	v_mfma_f32_16x16x32_bf16 v[40:43], v[170:173], v[186:189], v[40:43]
	v_mfma_f32_16x16x32_bf16 v[36:39], v[170:173], v[190:193], v[36:39]
	ds_read_b128 v[158:161], v213 offset:8192
	ds_read_b128 v[162:165], v213 offset:10240
	ds_read_b128 v[166:169], v213 offset:12288
	ds_read_b128 v[170:173], v213 offset:14336
	s_waitcnt lgkmcnt(4)
	v_mfma_f32_16x16x32_bf16 v[124:127], v[142:145], v[194:197], v[124:127]
	v_mfma_f32_16x16x32_bf16 v[120:123], v[142:145], v[198:201], v[120:123]
	v_mfma_f32_16x16x32_bf16 v[116:119], v[142:145], v[202:205], v[116:119]
	v_mfma_f32_16x16x32_bf16 v[112:115], v[142:145], v[206:209], v[112:115]
	v_mfma_f32_16x16x32_bf16 v[108:111], v[146:149], v[194:197], v[108:111]
	v_mfma_f32_16x16x32_bf16 v[104:107], v[146:149], v[198:201], v[104:107]
	v_mfma_f32_16x16x32_bf16 v[100:103], v[146:149], v[202:205], v[100:103]
	v_mfma_f32_16x16x32_bf16 v[96:99], v[146:149], v[206:209], v[96:99]
	v_mfma_f32_16x16x32_bf16 v[92:95], v[150:153], v[194:197], v[92:95]
	v_mfma_f32_16x16x32_bf16 v[88:91], v[150:153], v[198:201], v[88:91]
	v_mfma_f32_16x16x32_bf16 v[84:87], v[150:153], v[202:205], v[84:87]
	v_mfma_f32_16x16x32_bf16 v[80:83], v[150:153], v[206:209], v[80:83]
	v_mfma_f32_16x16x32_bf16 v[76:79], v[154:157], v[194:197], v[76:79]
	v_mfma_f32_16x16x32_bf16 v[72:75], v[154:157], v[198:201], v[72:75]
	v_mfma_f32_16x16x32_bf16 v[68:71], v[154:157], v[202:205], v[68:71]
	v_mfma_f32_16x16x32_bf16 v[64:67], v[154:157], v[206:209], v[64:67]
	s_add_u32 s48, s48, 0x80
	s_addc_u32 s49, s49, 0
	s_add_i32 s47, s47, 1
	s_branch .Lg7_top

.Lg8_top:
	s_waitcnt lgkmcnt(0)
	s_waitcnt vmcnt(0)
	s_barrier
	s_xor_b32 s59, s59, 0x10000
	s_mov_b32 m0, s59
	s_add_u32 s62, s60, s22
	s_addc_u32 s63, s61, s23
	global_load_lds_dwordx4 v178, s[62:63]
	s_add_u32 m0, s59, 0x2000
	s_add_u32 s62, s60, s36
	s_addc_u32 s63, s61, s37
	global_load_lds_dwordx4 v178, s[62:63]
	ds_read_b128 v[154:157], v180
	ds_read_b128 v[158:161], v180 offset:2048
	ds_read_b128 v[162:165], v180 offset:4096
	ds_read_b128 v[166:169], v180 offset:6144
	ds_read_b128 v[190:193], v223 offset:32768
	ds_read_b128 v[194:197], v223 offset:34816
	ds_read_b128 v[198:201], v223 offset:36864
	ds_read_b128 v[202:205], v223 offset:38912
	v_mfma_f32_16x16x32_bf16 v[60:63], v[170:173], v[206:209], v[60:63]
	v_mfma_f32_16x16x32_bf16 v[56:59], v[170:173], v[210:213], v[56:59]
	s_add_u32 m0, s59, 0x4000
	s_add_u32 s62, s60, s38
	s_addc_u32 s63, s61, s39
	global_load_lds_dwordx4 v178, s[62:63]
	v_mfma_f32_16x16x32_bf16 v[52:55], v[170:173], v[214:217], v[52:55]
	v_mfma_f32_16x16x32_bf16 v[44:47], v[170:173], v[218:221], v[44:47]
	s_add_u32 m0, s59, 0x6000
	s_add_u32 s62, s60, s40
	s_addc_u32 s63, s61, s41
	global_load_lds_dwordx4 v178, s[62:63]
	v_mfma_f32_16x16x32_bf16 v[36:39], v[174:177], v[206:209], v[36:39]
	v_mfma_f32_16x16x32_bf16 v[32:35], v[174:177], v[210:213], v[32:35]
	s_add_u32 m0, s59, 0x8000
	s_add_u32 s62, s60, s42
	s_addc_u32 s63, s61, s43
	global_load_lds_dwordx4 v179, s[62:63]
	v_mfma_f32_16x16x32_bf16 v[28:31], v[174:177], v[214:217], v[28:31]
	v_mfma_f32_16x16x32_bf16 v[24:27], v[174:177], v[218:221], v[24:27]
	s_add_u32 m0, s59, 0xa000
	s_add_u32 s62, s60, s44
	s_addc_u32 s63, s61, s45
	global_load_lds_dwordx4 v179, s[62:63]
	v_mfma_f32_16x16x32_bf16 v[20:23], v[182:185], v[206:209], v[20:23]
	v_mfma_f32_16x16x32_bf16 v[16:19], v[182:185], v[210:213], v[16:19]
	s_add_u32 m0, s59, 0xc000
	s_add_u32 s62, s60, s46
	s_addc_u32 s63, s61, s47
	global_load_lds_dwordx4 v179, s[62:63]
	v_mfma_f32_16x16x32_bf16 v[12:15], v[182:185], v[214:217], v[12:15]
	v_mfma_f32_16x16x32_bf16 v[8:11], v[182:185], v[218:221], v[8:11]
	s_add_u32 m0, s59, 0xe000
	s_add_u32 s62, s60, s48
	s_addc_u32 s63, s61, s49
	global_load_lds_dwordx4 v179, s[62:63]
	v_mfma_f32_16x16x32_bf16 v[4:7], v[186:189], v[206:209], v[4:7]
	v_mfma_f32_16x16x32_bf16 v[0:3], v[186:189], v[210:213], v[0:3]
	v_mfma_f32_16x16x32_bf16 v[48:51], v[186:189], v[214:217], v[48:51]
	v_mfma_f32_16x16x32_bf16 v[40:43], v[186:189], v[218:221], v[40:43]
.Lg8_entry:
	ds_read_b128 v[170:173], v180 offset:8192
	ds_read_b128 v[174:177], v180 offset:10240
	ds_read_b128 v[182:185], v180 offset:12288
	ds_read_b128 v[186:189], v180 offset:14336
	s_waitcnt lgkmcnt(4)
	v_mfma_f32_16x16x32_bf16 v[124:127], v[154:157], v[190:193], v[124:127]
	v_mfma_f32_16x16x32_bf16 v[120:123], v[154:157], v[194:197], v[120:123]
	v_mfma_f32_16x16x32_bf16 v[116:119], v[154:157], v[198:201], v[116:119]
	v_mfma_f32_16x16x32_bf16 v[112:115], v[154:157], v[202:205], v[112:115]
	v_mfma_f32_16x16x32_bf16 v[108:111], v[158:161], v[190:193], v[108:111]
	v_mfma_f32_16x16x32_bf16 v[104:107], v[158:161], v[194:197], v[104:107]
	v_mfma_f32_16x16x32_bf16 v[100:103], v[158:161], v[198:201], v[100:103]
	v_mfma_f32_16x16x32_bf16 v[96:99], v[158:161], v[202:205], v[96:99]
	v_mfma_f32_16x16x32_bf16 v[92:95], v[162:165], v[190:193], v[92:95]
	v_mfma_f32_16x16x32_bf16 v[88:91], v[162:165], v[194:197], v[88:91]
	v_mfma_f32_16x16x32_bf16 v[84:87], v[162:165], v[198:201], v[84:87]
	v_mfma_f32_16x16x32_bf16 v[80:83], v[162:165], v[202:205], v[80:83]
	v_mfma_f32_16x16x32_bf16 v[76:79], v[166:169], v[190:193], v[76:79]
	v_mfma_f32_16x16x32_bf16 v[72:75], v[166:169], v[194:197], v[72:75]
	v_mfma_f32_16x16x32_bf16 v[68:71], v[166:169], v[198:201], v[68:71]
	v_mfma_f32_16x16x32_bf16 v[64:67], v[166:169], v[202:205], v[64:67]
	ds_read_b128 v[154:157], v222
	ds_read_b128 v[158:161], v222 offset:2048
	ds_read_b128 v[162:165], v222 offset:4096
	ds_read_b128 v[166:169], v222 offset:6144
	ds_read_b128 v[206:209], v224 offset:32768
	ds_read_b128 v[210:213], v224 offset:34816
	ds_read_b128 v[214:217], v224 offset:36864
	ds_read_b128 v[218:221], v224 offset:38912
	s_waitcnt lgkmcnt(8)
	v_mfma_f32_16x16x32_bf16 v[60:63], v[170:173], v[190:193], v[60:63]
	v_mfma_f32_16x16x32_bf16 v[56:59], v[170:173], v[194:197], v[56:59]
	v_mfma_f32_16x16x32_bf16 v[52:55], v[170:173], v[198:201], v[52:55]
	v_mfma_f32_16x16x32_bf16 v[44:47], v[170:173], v[202:205], v[44:47]
	v_mfma_f32_16x16x32_bf16 v[36:39], v[174:177], v[190:193], v[36:39]
	v_mfma_f32_16x16x32_bf16 v[32:35], v[174:177], v[194:197], v[32:35]
	v_mfma_f32_16x16x32_bf16 v[28:31], v[174:177], v[198:201], v[28:31]
	v_mfma_f32_16x16x32_bf16 v[24:27], v[174:177], v[202:205], v[24:27]
	v_mfma_f32_16x16x32_bf16 v[20:23], v[182:185], v[190:193], v[20:23]
	v_mfma_f32_16x16x32_bf16 v[16:19], v[182:185], v[194:197], v[16:19]
	v_mfma_f32_16x16x32_bf16 v[12:15], v[182:185], v[198:201], v[12:15]
	v_mfma_f32_16x16x32_bf16 v[8:11], v[182:185], v[202:205], v[8:11]
	v_mfma_f32_16x16x32_bf16 v[4:7], v[186:189], v[190:193], v[4:7]
	v_mfma_f32_16x16x32_bf16 v[0:3], v[186:189], v[194:197], v[0:3]
	v_mfma_f32_16x16x32_bf16 v[48:51], v[186:189], v[198:201], v[48:51]
	v_mfma_f32_16x16x32_bf16 v[40:43], v[186:189], v[202:205], v[40:43]
	ds_read_b128 v[170:173], v222 offset:8192
	ds_read_b128 v[174:177], v222 offset:10240
	ds_read_b128 v[182:185], v222 offset:12288
	ds_read_b128 v[186:189], v222 offset:14336
	s_waitcnt lgkmcnt(4)
	v_mfma_f32_16x16x32_bf16 v[124:127], v[154:157], v[206:209], v[124:127]
	v_mfma_f32_16x16x32_bf16 v[120:123], v[154:157], v[210:213], v[120:123]
	v_mfma_f32_16x16x32_bf16 v[116:119], v[154:157], v[214:217], v[116:119]
	v_mfma_f32_16x16x32_bf16 v[112:115], v[154:157], v[218:221], v[112:115]
	v_mfma_f32_16x16x32_bf16 v[108:111], v[158:161], v[206:209], v[108:111]
	v_mfma_f32_16x16x32_bf16 v[104:107], v[158:161], v[210:213], v[104:107]
	v_mfma_f32_16x16x32_bf16 v[100:103], v[158:161], v[214:217], v[100:103]
	v_mfma_f32_16x16x32_bf16 v[96:99], v[158:161], v[218:221], v[96:99]
	v_mfma_f32_16x16x32_bf16 v[92:95], v[162:165], v[206:209], v[92:95]
	v_mfma_f32_16x16x32_bf16 v[88:91], v[162:165], v[210:213], v[88:91]
	v_mfma_f32_16x16x32_bf16 v[84:87], v[162:165], v[214:217], v[84:87]
	v_mfma_f32_16x16x32_bf16 v[80:83], v[162:165], v[218:221], v[80:83]
	v_mfma_f32_16x16x32_bf16 v[76:79], v[166:169], v[206:209], v[76:79]
	v_mfma_f32_16x16x32_bf16 v[72:75], v[166:169], v[210:213], v[72:75]
	v_mfma_f32_16x16x32_bf16 v[68:71], v[166:169], v[214:217], v[68:71]
	v_mfma_f32_16x16x32_bf16 v[64:67], v[166:169], v[218:221], v[64:67]
	s_add_u32 s60, s60, 0x80
	s_addc_u32 s61, s61, 0
	s_add_i32 s57, s57, 1
	s_cmp_lt_u32 s57, 15
	s_cbranch_scc0 .Lg8_last
	s_waitcnt lgkmcnt(0)
	s_waitcnt vmcnt(0)
	s_barrier
	s_xor_b32 s59, s59, 0x10000
	s_mov_b32 m0, s59
	s_add_u32 s62, s60, s22
	s_addc_u32 s63, s61, s23
	global_load_lds_dwordx4 v178, s[62:63]
	s_add_u32 m0, s59, 0x2000
	s_add_u32 s62, s60, s36
	s_addc_u32 s63, s61, s37
	global_load_lds_dwordx4 v178, s[62:63]
	ds_read_b128 v[154:157], v225
	ds_read_b128 v[158:161], v225 offset:2048
	ds_read_b128 v[162:165], v225 offset:4096
	ds_read_b128 v[166:169], v225 offset:6144
	ds_read_b128 v[190:193], v227 offset:32768
	ds_read_b128 v[194:197], v227 offset:34816
	ds_read_b128 v[198:201], v227 offset:36864
	ds_read_b128 v[202:205], v227 offset:38912
	v_mfma_f32_16x16x32_bf16 v[60:63], v[170:173], v[206:209], v[60:63]
	v_mfma_f32_16x16x32_bf16 v[56:59], v[170:173], v[210:213], v[56:59]
	s_add_u32 m0, s59, 0x4000
	s_add_u32 s62, s60, s38
	s_addc_u32 s63, s61, s39
	global_load_lds_dwordx4 v178, s[62:63]
	v_mfma_f32_16x16x32_bf16 v[52:55], v[170:173], v[214:217], v[52:55]
	v_mfma_f32_16x16x32_bf16 v[44:47], v[170:173], v[218:221], v[44:47]
	s_add_u32 m0, s59, 0x6000
	s_add_u32 s62, s60, s40
	s_addc_u32 s63, s61, s41
	global_load_lds_dwordx4 v178, s[62:63]
	v_mfma_f32_16x16x32_bf16 v[36:39], v[174:177], v[206:209], v[36:39]
	v_mfma_f32_16x16x32_bf16 v[32:35], v[174:177], v[210:213], v[32:35]
	s_add_u32 m0, s59, 0x8000
	s_add_u32 s62, s60, s42
	s_addc_u32 s63, s61, s43
	global_load_lds_dwordx4 v179, s[62:63]
	v_mfma_f32_16x16x32_bf16 v[28:31], v[174:177], v[214:217], v[28:31]
	v_mfma_f32_16x16x32_bf16 v[24:27], v[174:177], v[218:221], v[24:27]
	s_add_u32 m0, s59, 0xa000
	s_add_u32 s62, s60, s44
	s_addc_u32 s63, s61, s45
	global_load_lds_dwordx4 v179, s[62:63]
	v_mfma_f32_16x16x32_bf16 v[20:23], v[182:185], v[206:209], v[20:23]
	v_mfma_f32_16x16x32_bf16 v[16:19], v[182:185], v[210:213], v[16:19]
	s_add_u32 m0, s59, 0xc000
	s_add_u32 s62, s60, s46
	s_addc_u32 s63, s61, s47
	global_load_lds_dwordx4 v179, s[62:63]
	v_mfma_f32_16x16x32_bf16 v[12:15], v[182:185], v[214:217], v[12:15]
	v_mfma_f32_16x16x32_bf16 v[8:11], v[182:185], v[218:221], v[8:11]
	s_add_u32 m0, s59, 0xe000
	s_add_u32 s62, s60, s48
	s_addc_u32 s63, s61, s49
	global_load_lds_dwordx4 v179, s[62:63]
	v_mfma_f32_16x16x32_bf16 v[4:7], v[186:189], v[206:209], v[4:7]
	v_mfma_f32_16x16x32_bf16 v[0:3], v[186:189], v[210:213], v[0:3]
	v_mfma_f32_16x16x32_bf16 v[48:51], v[186:189], v[214:217], v[48:51]
	v_mfma_f32_16x16x32_bf16 v[40:43], v[186:189], v[218:221], v[40:43]
	ds_read_b128 v[170:173], v225 offset:8192
	ds_read_b128 v[174:177], v225 offset:10240
	ds_read_b128 v[182:185], v225 offset:12288
	ds_read_b128 v[186:189], v225 offset:14336
	s_waitcnt lgkmcnt(4)
	v_mfma_f32_16x16x32_bf16 v[124:127], v[154:157], v[190:193], v[124:127]
	v_mfma_f32_16x16x32_bf16 v[120:123], v[154:157], v[194:197], v[120:123]
	v_mfma_f32_16x16x32_bf16 v[116:119], v[154:157], v[198:201], v[116:119]
	v_mfma_f32_16x16x32_bf16 v[112:115], v[154:157], v[202:205], v[112:115]
	v_mfma_f32_16x16x32_bf16 v[108:111], v[158:161], v[190:193], v[108:111]
	v_mfma_f32_16x16x32_bf16 v[104:107], v[158:161], v[194:197], v[104:107]
	v_mfma_f32_16x16x32_bf16 v[100:103], v[158:161], v[198:201], v[100:103]
	v_mfma_f32_16x16x32_bf16 v[96:99], v[158:161], v[202:205], v[96:99]
	v_mfma_f32_16x16x32_bf16 v[92:95], v[162:165], v[190:193], v[92:95]
	v_mfma_f32_16x16x32_bf16 v[88:91], v[162:165], v[194:197], v[88:91]
	v_mfma_f32_16x16x32_bf16 v[84:87], v[162:165], v[198:201], v[84:87]
	v_mfma_f32_16x16x32_bf16 v[80:83], v[162:165], v[202:205], v[80:83]
	v_mfma_f32_16x16x32_bf16 v[76:79], v[166:169], v[190:193], v[76:79]
	v_mfma_f32_16x16x32_bf16 v[72:75], v[166:169], v[194:197], v[72:75]
	v_mfma_f32_16x16x32_bf16 v[68:71], v[166:169], v[198:201], v[68:71]
	v_mfma_f32_16x16x32_bf16 v[64:67], v[166:169], v[202:205], v[64:67]
	ds_read_b128 v[154:157], v226
	ds_read_b128 v[158:161], v226 offset:2048
	ds_read_b128 v[162:165], v226 offset:4096
	ds_read_b128 v[166:169], v226 offset:6144
	ds_read_b128 v[206:209], v228 offset:32768
	ds_read_b128 v[210:213], v228 offset:34816
	ds_read_b128 v[214:217], v228 offset:36864
	ds_read_b128 v[218:221], v228 offset:38912
	s_waitcnt lgkmcnt(8)
	v_mfma_f32_16x16x32_bf16 v[60:63], v[170:173], v[190:193], v[60:63]
	v_mfma_f32_16x16x32_bf16 v[56:59], v[170:173], v[194:197], v[56:59]
	v_mfma_f32_16x16x32_bf16 v[52:55], v[170:173], v[198:201], v[52:55]
	v_mfma_f32_16x16x32_bf16 v[44:47], v[170:173], v[202:205], v[44:47]
	v_mfma_f32_16x16x32_bf16 v[36:39], v[174:177], v[190:193], v[36:39]
	v_mfma_f32_16x16x32_bf16 v[32:35], v[174:177], v[194:197], v[32:35]
	v_mfma_f32_16x16x32_bf16 v[28:31], v[174:177], v[198:201], v[28:31]
	v_mfma_f32_16x16x32_bf16 v[24:27], v[174:177], v[202:205], v[24:27]
	v_mfma_f32_16x16x32_bf16 v[20:23], v[182:185], v[190:193], v[20:23]
	v_mfma_f32_16x16x32_bf16 v[16:19], v[182:185], v[194:197], v[16:19]
	v_mfma_f32_16x16x32_bf16 v[12:15], v[182:185], v[198:201], v[12:15]
	v_mfma_f32_16x16x32_bf16 v[8:11], v[182:185], v[202:205], v[8:11]
	v_mfma_f32_16x16x32_bf16 v[4:7], v[186:189], v[190:193], v[4:7]
	v_mfma_f32_16x16x32_bf16 v[0:3], v[186:189], v[194:197], v[0:3]
	v_mfma_f32_16x16x32_bf16 v[48:51], v[186:189], v[198:201], v[48:51]
	v_mfma_f32_16x16x32_bf16 v[40:43], v[186:189], v[202:205], v[40:43]
	ds_read_b128 v[170:173], v226 offset:8192
	ds_read_b128 v[174:177], v226 offset:10240
	ds_read_b128 v[182:185], v226 offset:12288
	ds_read_b128 v[186:189], v226 offset:14336
	s_waitcnt lgkmcnt(4)
	v_mfma_f32_16x16x32_bf16 v[124:127], v[154:157], v[206:209], v[124:127]
	v_mfma_f32_16x16x32_bf16 v[120:123], v[154:157], v[210:213], v[120:123]
	v_mfma_f32_16x16x32_bf16 v[116:119], v[154:157], v[214:217], v[116:119]
	v_mfma_f32_16x16x32_bf16 v[112:115], v[154:157], v[218:221], v[112:115]
	v_mfma_f32_16x16x32_bf16 v[108:111], v[158:161], v[206:209], v[108:111]
	v_mfma_f32_16x16x32_bf16 v[104:107], v[158:161], v[210:213], v[104:107]
	v_mfma_f32_16x16x32_bf16 v[100:103], v[158:161], v[214:217], v[100:103]
	v_mfma_f32_16x16x32_bf16 v[96:99], v[158:161], v[218:221], v[96:99]
	v_mfma_f32_16x16x32_bf16 v[92:95], v[162:165], v[206:209], v[92:95]
	v_mfma_f32_16x16x32_bf16 v[88:91], v[162:165], v[210:213], v[88:91]
	v_mfma_f32_16x16x32_bf16 v[84:87], v[162:165], v[214:217], v[84:87]
	v_mfma_f32_16x16x32_bf16 v[80:83], v[162:165], v[218:221], v[80:83]
	v_mfma_f32_16x16x32_bf16 v[76:79], v[166:169], v[206:209], v[76:79]
	v_mfma_f32_16x16x32_bf16 v[72:75], v[166:169], v[210:213], v[72:75]
	v_mfma_f32_16x16x32_bf16 v[68:71], v[166:169], v[214:217], v[68:71]
	v_mfma_f32_16x16x32_bf16 v[64:67], v[166:169], v[218:221], v[64:67]
	s_add_u32 s60, s60, 0x80
	s_addc_u32 s61, s61, 0
	s_add_i32 s57, s57, 1
	s_branch .Lg8_top

.Lg9_top:
	s_waitcnt lgkmcnt(0)
	s_waitcnt vmcnt(0)
	s_barrier
	s_xor_b32 s59, s59, 0x10000
	s_mov_b32 m0, s59
	s_add_u32 s46, s44, s12
	s_addc_u32 s47, s45, s13
	global_load_lds_dwordx4 v178, s[46:47]
	s_add_u32 m0, s59, 0x2000
	s_add_u32 s46, s44, s14
	s_addc_u32 s47, s45, s15
	global_load_lds_dwordx4 v178, s[46:47]
	ds_read_b128 v[142:145], v141
	ds_read_b128 v[146:149], v141 offset:2048
	ds_read_b128 v[150:153], v141 offset:4096
	ds_read_b128 v[154:157], v141 offset:6144
	ds_read_b128 v[174:177], v210 offset:32768
	ds_read_b128 v[182:185], v210 offset:34816
	ds_read_b128 v[186:189], v210 offset:36864
	ds_read_b128 v[190:193], v210 offset:38912
	v_mfma_f32_16x16x32_bf16 v[60:63], v[158:161], v[194:197], v[60:63]
	v_mfma_f32_16x16x32_bf16 v[56:59], v[158:161], v[198:201], v[56:59]
	s_add_u32 m0, s59, 0x4000
	s_add_u32 s46, s44, s16
	s_addc_u32 s47, s45, s17
	global_load_lds_dwordx4 v178, s[46:47]
	v_mfma_f32_16x16x32_bf16 v[52:55], v[158:161], v[202:205], v[52:55]
	v_mfma_f32_16x16x32_bf16 v[48:51], v[158:161], v[206:209], v[48:51]
	s_add_u32 m0, s59, 0x6000
	s_add_u32 s46, s44, s18
	s_addc_u32 s47, s45, s19
	global_load_lds_dwordx4 v178, s[46:47]
	v_mfma_f32_16x16x32_bf16 v[44:47], v[162:165], v[194:197], v[44:47]
	v_mfma_f32_16x16x32_bf16 v[32:35], v[162:165], v[198:201], v[32:35]
	s_add_u32 m0, s59, 0x8000
	s_add_u32 s46, s44, s22
	s_addc_u32 s47, s45, s23
	global_load_lds_dwordx4 v179, s[46:47]
	v_mfma_f32_16x16x32_bf16 v[28:31], v[162:165], v[202:205], v[28:31]
	v_mfma_f32_16x16x32_bf16 v[24:27], v[162:165], v[206:209], v[24:27]
	s_add_u32 m0, s59, 0xa000
	s_add_u32 s46, s44, s36
	s_addc_u32 s47, s45, s37
	global_load_lds_dwordx4 v179, s[46:47]
	v_mfma_f32_16x16x32_bf16 v[20:23], v[166:169], v[194:197], v[20:23]
	v_mfma_f32_16x16x32_bf16 v[16:19], v[166:169], v[198:201], v[16:19]
	s_add_u32 m0, s59, 0xc000
	s_add_u32 s46, s44, s38
	s_addc_u32 s47, s45, s39
	global_load_lds_dwordx4 v179, s[46:47]
	v_mfma_f32_16x16x32_bf16 v[12:15], v[166:169], v[202:205], v[12:15]
	v_mfma_f32_16x16x32_bf16 v[8:11], v[166:169], v[206:209], v[8:11]
	s_add_u32 m0, s59, 0xe000
	s_add_u32 s46, s44, s40
	s_addc_u32 s47, s45, s41
	global_load_lds_dwordx4 v179, s[46:47]
	v_mfma_f32_16x16x32_bf16 v[4:7], v[170:173], v[194:197], v[4:7]
	v_mfma_f32_16x16x32_bf16 v[0:3], v[170:173], v[198:201], v[0:3]
	v_mfma_f32_16x16x32_bf16 v[40:43], v[170:173], v[202:205], v[40:43]
	v_mfma_f32_16x16x32_bf16 v[36:39], v[170:173], v[206:209], v[36:39]
.Lg9_entry:
	ds_read_b128 v[158:161], v141 offset:8192
	ds_read_b128 v[162:165], v141 offset:10240
	ds_read_b128 v[166:169], v141 offset:12288
	ds_read_b128 v[170:173], v141 offset:14336
	s_waitcnt lgkmcnt(4)
	v_mfma_f32_16x16x32_bf16 v[124:127], v[142:145], v[174:177], v[124:127]
	v_mfma_f32_16x16x32_bf16 v[120:123], v[142:145], v[182:185], v[120:123]
	v_mfma_f32_16x16x32_bf16 v[116:119], v[142:145], v[186:189], v[116:119]
	v_mfma_f32_16x16x32_bf16 v[112:115], v[142:145], v[190:193], v[112:115]
	v_mfma_f32_16x16x32_bf16 v[108:111], v[146:149], v[174:177], v[108:111]
	v_mfma_f32_16x16x32_bf16 v[104:107], v[146:149], v[182:185], v[104:107]
	v_mfma_f32_16x16x32_bf16 v[100:103], v[146:149], v[186:189], v[100:103]
	v_mfma_f32_16x16x32_bf16 v[96:99], v[146:149], v[190:193], v[96:99]
	v_mfma_f32_16x16x32_bf16 v[92:95], v[150:153], v[174:177], v[92:95]
	v_mfma_f32_16x16x32_bf16 v[88:91], v[150:153], v[182:185], v[88:91]
	v_mfma_f32_16x16x32_bf16 v[84:87], v[150:153], v[186:189], v[84:87]
	v_mfma_f32_16x16x32_bf16 v[80:83], v[150:153], v[190:193], v[80:83]
	v_mfma_f32_16x16x32_bf16 v[76:79], v[154:157], v[174:177], v[76:79]
	v_mfma_f32_16x16x32_bf16 v[72:75], v[154:157], v[182:185], v[72:75]
	v_mfma_f32_16x16x32_bf16 v[68:71], v[154:157], v[186:189], v[68:71]
	v_mfma_f32_16x16x32_bf16 v[64:67], v[154:157], v[190:193], v[64:67]
	ds_read_b128 v[142:145], v180
	ds_read_b128 v[146:149], v180 offset:2048
	ds_read_b128 v[150:153], v180 offset:4096
	ds_read_b128 v[154:157], v180 offset:6144
	ds_read_b128 v[194:197], v211 offset:32768
	ds_read_b128 v[198:201], v211 offset:34816
	ds_read_b128 v[202:205], v211 offset:36864
	ds_read_b128 v[206:209], v211 offset:38912
	s_waitcnt lgkmcnt(8)
	v_mfma_f32_16x16x32_bf16 v[60:63], v[158:161], v[174:177], v[60:63]
	v_mfma_f32_16x16x32_bf16 v[56:59], v[158:161], v[182:185], v[56:59]
	v_mfma_f32_16x16x32_bf16 v[52:55], v[158:161], v[186:189], v[52:55]
	v_mfma_f32_16x16x32_bf16 v[48:51], v[158:161], v[190:193], v[48:51]
	v_mfma_f32_16x16x32_bf16 v[44:47], v[162:165], v[174:177], v[44:47]
	v_mfma_f32_16x16x32_bf16 v[32:35], v[162:165], v[182:185], v[32:35]
	v_mfma_f32_16x16x32_bf16 v[28:31], v[162:165], v[186:189], v[28:31]
	v_mfma_f32_16x16x32_bf16 v[24:27], v[162:165], v[190:193], v[24:27]
	v_mfma_f32_16x16x32_bf16 v[20:23], v[166:169], v[174:177], v[20:23]
	v_mfma_f32_16x16x32_bf16 v[16:19], v[166:169], v[182:185], v[16:19]
	v_mfma_f32_16x16x32_bf16 v[12:15], v[166:169], v[186:189], v[12:15]
	v_mfma_f32_16x16x32_bf16 v[8:11], v[166:169], v[190:193], v[8:11]
	v_mfma_f32_16x16x32_bf16 v[4:7], v[170:173], v[174:177], v[4:7]
	v_mfma_f32_16x16x32_bf16 v[0:3], v[170:173], v[182:185], v[0:3]
	v_mfma_f32_16x16x32_bf16 v[40:43], v[170:173], v[186:189], v[40:43]
	v_mfma_f32_16x16x32_bf16 v[36:39], v[170:173], v[190:193], v[36:39]
	ds_read_b128 v[158:161], v180 offset:8192
	ds_read_b128 v[162:165], v180 offset:10240
	ds_read_b128 v[166:169], v180 offset:12288
	ds_read_b128 v[170:173], v180 offset:14336
	s_waitcnt lgkmcnt(4)
	v_mfma_f32_16x16x32_bf16 v[124:127], v[142:145], v[194:197], v[124:127]
	v_mfma_f32_16x16x32_bf16 v[120:123], v[142:145], v[198:201], v[120:123]
	v_mfma_f32_16x16x32_bf16 v[116:119], v[142:145], v[202:205], v[116:119]
	v_mfma_f32_16x16x32_bf16 v[112:115], v[142:145], v[206:209], v[112:115]
	v_mfma_f32_16x16x32_bf16 v[108:111], v[146:149], v[194:197], v[108:111]
	v_mfma_f32_16x16x32_bf16 v[104:107], v[146:149], v[198:201], v[104:107]
	v_mfma_f32_16x16x32_bf16 v[100:103], v[146:149], v[202:205], v[100:103]
	v_mfma_f32_16x16x32_bf16 v[96:99], v[146:149], v[206:209], v[96:99]
	v_mfma_f32_16x16x32_bf16 v[92:95], v[150:153], v[194:197], v[92:95]
	v_mfma_f32_16x16x32_bf16 v[88:91], v[150:153], v[198:201], v[88:91]
	v_mfma_f32_16x16x32_bf16 v[84:87], v[150:153], v[202:205], v[84:87]
	v_mfma_f32_16x16x32_bf16 v[80:83], v[150:153], v[206:209], v[80:83]
	v_mfma_f32_16x16x32_bf16 v[76:79], v[154:157], v[194:197], v[76:79]
	v_mfma_f32_16x16x32_bf16 v[72:75], v[154:157], v[198:201], v[72:75]
	v_mfma_f32_16x16x32_bf16 v[68:71], v[154:157], v[202:205], v[68:71]
	v_mfma_f32_16x16x32_bf16 v[64:67], v[154:157], v[206:209], v[64:67]
	s_add_u32 s44, s44, 0x80
	s_addc_u32 s45, s45, 0
	s_add_i32 s43, s43, 1
	s_cmp_lt_u32 s43, 31
	s_cbranch_scc0 .Lg9_last
	s_waitcnt lgkmcnt(0)
	s_waitcnt vmcnt(0)
	s_barrier
	s_xor_b32 s59, s59, 0x10000
	s_mov_b32 m0, s59
	s_add_u32 s46, s44, s12
	s_addc_u32 s47, s45, s13
	global_load_lds_dwordx4 v178, s[46:47]
	s_add_u32 m0, s59, 0x2000
	s_add_u32 s46, s44, s14
	s_addc_u32 s47, s45, s15
	global_load_lds_dwordx4 v178, s[46:47]
	ds_read_b128 v[142:145], v212
	ds_read_b128 v[146:149], v212 offset:2048
	ds_read_b128 v[150:153], v212 offset:4096
	ds_read_b128 v[154:157], v212 offset:6144
	ds_read_b128 v[174:177], v214 offset:32768
	ds_read_b128 v[182:185], v214 offset:34816
	ds_read_b128 v[186:189], v214 offset:36864
	ds_read_b128 v[190:193], v214 offset:38912
	v_mfma_f32_16x16x32_bf16 v[60:63], v[158:161], v[194:197], v[60:63]
	v_mfma_f32_16x16x32_bf16 v[56:59], v[158:161], v[198:201], v[56:59]
	s_add_u32 m0, s59, 0x4000
	s_add_u32 s46, s44, s16
	s_addc_u32 s47, s45, s17
	global_load_lds_dwordx4 v178, s[46:47]
	v_mfma_f32_16x16x32_bf16 v[52:55], v[158:161], v[202:205], v[52:55]
	v_mfma_f32_16x16x32_bf16 v[48:51], v[158:161], v[206:209], v[48:51]
	s_add_u32 m0, s59, 0x6000
	s_add_u32 s46, s44, s18
	s_addc_u32 s47, s45, s19
	global_load_lds_dwordx4 v178, s[46:47]
	v_mfma_f32_16x16x32_bf16 v[44:47], v[162:165], v[194:197], v[44:47]
	v_mfma_f32_16x16x32_bf16 v[32:35], v[162:165], v[198:201], v[32:35]
	s_add_u32 m0, s59, 0x8000
	s_add_u32 s46, s44, s22
	s_addc_u32 s47, s45, s23
	global_load_lds_dwordx4 v179, s[46:47]
	v_mfma_f32_16x16x32_bf16 v[28:31], v[162:165], v[202:205], v[28:31]
	v_mfma_f32_16x16x32_bf16 v[24:27], v[162:165], v[206:209], v[24:27]
	s_add_u32 m0, s59, 0xa000
	s_add_u32 s46, s44, s36
	s_addc_u32 s47, s45, s37
	global_load_lds_dwordx4 v179, s[46:47]
	v_mfma_f32_16x16x32_bf16 v[20:23], v[166:169], v[194:197], v[20:23]
	v_mfma_f32_16x16x32_bf16 v[16:19], v[166:169], v[198:201], v[16:19]
	s_add_u32 m0, s59, 0xc000
	s_add_u32 s46, s44, s38
	s_addc_u32 s47, s45, s39
	global_load_lds_dwordx4 v179, s[46:47]
	v_mfma_f32_16x16x32_bf16 v[12:15], v[166:169], v[202:205], v[12:15]
	v_mfma_f32_16x16x32_bf16 v[8:11], v[166:169], v[206:209], v[8:11]
	s_add_u32 m0, s59, 0xe000
	s_add_u32 s46, s44, s40
	s_addc_u32 s47, s45, s41
	global_load_lds_dwordx4 v179, s[46:47]
	v_mfma_f32_16x16x32_bf16 v[4:7], v[170:173], v[194:197], v[4:7]
	v_mfma_f32_16x16x32_bf16 v[0:3], v[170:173], v[198:201], v[0:3]
	v_mfma_f32_16x16x32_bf16 v[40:43], v[170:173], v[202:205], v[40:43]
	v_mfma_f32_16x16x32_bf16 v[36:39], v[170:173], v[206:209], v[36:39]
	ds_read_b128 v[158:161], v212 offset:8192
	ds_read_b128 v[162:165], v212 offset:10240
	ds_read_b128 v[166:169], v212 offset:12288
	ds_read_b128 v[170:173], v212 offset:14336
	s_waitcnt lgkmcnt(4)
	v_mfma_f32_16x16x32_bf16 v[124:127], v[142:145], v[174:177], v[124:127]
	v_mfma_f32_16x16x32_bf16 v[120:123], v[142:145], v[182:185], v[120:123]
	v_mfma_f32_16x16x32_bf16 v[116:119], v[142:145], v[186:189], v[116:119]
	v_mfma_f32_16x16x32_bf16 v[112:115], v[142:145], v[190:193], v[112:115]
	v_mfma_f32_16x16x32_bf16 v[108:111], v[146:149], v[174:177], v[108:111]
	v_mfma_f32_16x16x32_bf16 v[104:107], v[146:149], v[182:185], v[104:107]
	v_mfma_f32_16x16x32_bf16 v[100:103], v[146:149], v[186:189], v[100:103]
	v_mfma_f32_16x16x32_bf16 v[96:99], v[146:149], v[190:193], v[96:99]
	v_mfma_f32_16x16x32_bf16 v[92:95], v[150:153], v[174:177], v[92:95]
	v_mfma_f32_16x16x32_bf16 v[88:91], v[150:153], v[182:185], v[88:91]
	v_mfma_f32_16x16x32_bf16 v[84:87], v[150:153], v[186:189], v[84:87]
	v_mfma_f32_16x16x32_bf16 v[80:83], v[150:153], v[190:193], v[80:83]
	v_mfma_f32_16x16x32_bf16 v[76:79], v[154:157], v[174:177], v[76:79]
	v_mfma_f32_16x16x32_bf16 v[72:75], v[154:157], v[182:185], v[72:75]
	v_mfma_f32_16x16x32_bf16 v[68:71], v[154:157], v[186:189], v[68:71]
	v_mfma_f32_16x16x32_bf16 v[64:67], v[154:157], v[190:193], v[64:67]
	ds_read_b128 v[142:145], v213
	ds_read_b128 v[146:149], v213 offset:2048
	ds_read_b128 v[150:153], v213 offset:4096
	ds_read_b128 v[154:157], v213 offset:6144
	ds_read_b128 v[194:197], v215 offset:32768
	ds_read_b128 v[198:201], v215 offset:34816
	ds_read_b128 v[202:205], v215 offset:36864
	ds_read_b128 v[206:209], v215 offset:38912
	s_waitcnt lgkmcnt(8)
	v_mfma_f32_16x16x32_bf16 v[60:63], v[158:161], v[174:177], v[60:63]
	v_mfma_f32_16x16x32_bf16 v[56:59], v[158:161], v[182:185], v[56:59]
	v_mfma_f32_16x16x32_bf16 v[52:55], v[158:161], v[186:189], v[52:55]
	v_mfma_f32_16x16x32_bf16 v[48:51], v[158:161], v[190:193], v[48:51]
	v_mfma_f32_16x16x32_bf16 v[44:47], v[162:165], v[174:177], v[44:47]
	v_mfma_f32_16x16x32_bf16 v[32:35], v[162:165], v[182:185], v[32:35]
	v_mfma_f32_16x16x32_bf16 v[28:31], v[162:165], v[186:189], v[28:31]
	v_mfma_f32_16x16x32_bf16 v[24:27], v[162:165], v[190:193], v[24:27]
	v_mfma_f32_16x16x32_bf16 v[20:23], v[166:169], v[174:177], v[20:23]
	v_mfma_f32_16x16x32_bf16 v[16:19], v[166:169], v[182:185], v[16:19]
	v_mfma_f32_16x16x32_bf16 v[12:15], v[166:169], v[186:189], v[12:15]
	v_mfma_f32_16x16x32_bf16 v[8:11], v[166:169], v[190:193], v[8:11]
	v_mfma_f32_16x16x32_bf16 v[4:7], v[170:173], v[174:177], v[4:7]
	v_mfma_f32_16x16x32_bf16 v[0:3], v[170:173], v[182:185], v[0:3]
	v_mfma_f32_16x16x32_bf16 v[40:43], v[170:173], v[186:189], v[40:43]
	v_mfma_f32_16x16x32_bf16 v[36:39], v[170:173], v[190:193], v[36:39]
	ds_read_b128 v[158:161], v213 offset:8192
	ds_read_b128 v[162:165], v213 offset:10240
	ds_read_b128 v[166:169], v213 offset:12288
	ds_read_b128 v[170:173], v213 offset:14336
	s_waitcnt lgkmcnt(4)
	v_mfma_f32_16x16x32_bf16 v[124:127], v[142:145], v[194:197], v[124:127]
	v_mfma_f32_16x16x32_bf16 v[120:123], v[142:145], v[198:201], v[120:123]
	v_mfma_f32_16x16x32_bf16 v[116:119], v[142:145], v[202:205], v[116:119]
	v_mfma_f32_16x16x32_bf16 v[112:115], v[142:145], v[206:209], v[112:115]
	v_mfma_f32_16x16x32_bf16 v[108:111], v[146:149], v[194:197], v[108:111]
	v_mfma_f32_16x16x32_bf16 v[104:107], v[146:149], v[198:201], v[104:107]
	v_mfma_f32_16x16x32_bf16 v[100:103], v[146:149], v[202:205], v[100:103]
	v_mfma_f32_16x16x32_bf16 v[96:99], v[146:149], v[206:209], v[96:99]
	v_mfma_f32_16x16x32_bf16 v[92:95], v[150:153], v[194:197], v[92:95]
	v_mfma_f32_16x16x32_bf16 v[88:91], v[150:153], v[198:201], v[88:91]
	v_mfma_f32_16x16x32_bf16 v[84:87], v[150:153], v[202:205], v[84:87]
	v_mfma_f32_16x16x32_bf16 v[80:83], v[150:153], v[206:209], v[80:83]
	v_mfma_f32_16x16x32_bf16 v[76:79], v[154:157], v[194:197], v[76:79]
	v_mfma_f32_16x16x32_bf16 v[72:75], v[154:157], v[198:201], v[72:75]
	v_mfma_f32_16x16x32_bf16 v[68:71], v[154:157], v[202:205], v[68:71]
	v_mfma_f32_16x16x32_bf16 v[64:67], v[154:157], v[206:209], v[64:67]
	s_add_u32 s44, s44, 0x80
	s_addc_u32 s45, s45, 0
	s_add_i32 s43, s43, 1
	s_branch .Lg9_top

.Lg10_top:
	s_waitcnt lgkmcnt(0)
	s_waitcnt vmcnt(0)
	s_barrier
	s_xor_b32 s57, s57, 0x10000
	s_mov_b32 m0, s57
	s_add_u32 s46, s44, s14
	s_addc_u32 s47, s45, s15
	global_load_lds_dwordx4 v144, s[46:47]
	s_add_u32 m0, s57, 0x2000
	s_add_u32 s46, s44, s16
	s_addc_u32 s47, s45, s17
	global_load_lds_dwordx4 v144, s[46:47]
	ds_read_b128 v[156:159], v143
	ds_read_b128 v[160:163], v143 offset:2048
	ds_read_b128 v[164:167], v143 offset:4096
	ds_read_b128 v[168:171], v143 offset:6144
	ds_read_b128 v[190:193], v180 offset:32768
	ds_read_b128 v[194:197], v180 offset:34816
	ds_read_b128 v[198:201], v180 offset:36864
	ds_read_b128 v[202:205], v180 offset:38912
	v_mfma_f32_16x16x32_bf16 v[60:63], v[172:175], v[206:209], v[60:63]
	v_mfma_f32_16x16x32_bf16 v[52:55], v[172:175], v[210:213], v[52:55]
	s_add_u32 m0, s57, 0x4000
	s_add_u32 s46, s44, s18
	s_addc_u32 s47, s45, s19
	global_load_lds_dwordx4 v144, s[46:47]
	v_mfma_f32_16x16x32_bf16 v[56:59], v[172:175], v[214:217], v[56:59]
	v_mfma_f32_16x16x32_bf16 v[48:51], v[172:175], v[218:221], v[48:51]
	s_add_u32 m0, s57, 0x6000
	s_add_u32 s46, s44, s22
	s_addc_u32 s47, s45, s23
	global_load_lds_dwordx4 v144, s[46:47]
	v_mfma_f32_16x16x32_bf16 v[44:47], v[176:179], v[206:209], v[44:47]
	v_mfma_f32_16x16x32_bf16 v[36:39], v[176:179], v[210:213], v[36:39]
	s_add_u32 m0, s57, 0x8000
	s_add_u32 s46, s44, s30
	s_addc_u32 s47, s45, s31
	global_load_lds_dwordx4 v145, s[46:47]
	v_mfma_f32_16x16x32_bf16 v[40:43], v[176:179], v[214:217], v[40:43]
	v_mfma_f32_16x16x32_bf16 v[32:35], v[176:179], v[218:221], v[32:35]
	s_add_u32 m0, s57, 0xa000
	s_add_u32 s46, s44, s36
	s_addc_u32 s47, s45, s37
	global_load_lds_dwordx4 v145, s[46:47]
	v_mfma_f32_16x16x32_bf16 v[28:31], v[182:185], v[206:209], v[28:31]
	v_mfma_f32_16x16x32_bf16 v[16:19], v[182:185], v[210:213], v[16:19]
	s_add_u32 m0, s57, 0xc000
	s_add_u32 s46, s44, s38
	s_addc_u32 s47, s45, s39
	global_load_lds_dwordx4 v145, s[46:47]
	v_mfma_f32_16x16x32_bf16 v[24:27], v[182:185], v[214:217], v[24:27]
	v_mfma_f32_16x16x32_bf16 v[12:15], v[182:185], v[218:221], v[12:15]
	s_add_u32 m0, s57, 0xe000
	s_add_u32 s46, s44, s40
	s_addc_u32 s47, s45, s41
	global_load_lds_dwordx4 v145, s[46:47]
	v_mfma_f32_16x16x32_bf16 v[4:7], v[186:189], v[206:209], v[4:7]
	v_mfma_f32_16x16x32_bf16 v[0:3], v[186:189], v[210:213], v[0:3]
	v_mfma_f32_16x16x32_bf16 v[20:23], v[186:189], v[214:217], v[20:23]
	v_mfma_f32_16x16x32_bf16 v[8:11], v[186:189], v[218:221], v[8:11]
.Lg10_entry:
	ds_read_b128 v[172:175], v143 offset:8192
	ds_read_b128 v[176:179], v143 offset:10240
	ds_read_b128 v[182:185], v143 offset:12288
	ds_read_b128 v[186:189], v143 offset:14336
	s_waitcnt lgkmcnt(4)
	v_mfma_f32_16x16x32_bf16 v[124:127], v[156:159], v[190:193], v[124:127]
	v_mfma_f32_16x16x32_bf16 v[116:119], v[156:159], v[194:197], v[116:119]
	v_mfma_f32_16x16x32_bf16 v[120:123], v[156:159], v[198:201], v[120:123]
	v_mfma_f32_16x16x32_bf16 v[112:115], v[156:159], v[202:205], v[112:115]
	v_mfma_f32_16x16x32_bf16 v[108:111], v[160:163], v[190:193], v[108:111]
	v_mfma_f32_16x16x32_bf16 v[100:103], v[160:163], v[194:197], v[100:103]
	v_mfma_f32_16x16x32_bf16 v[104:107], v[160:163], v[198:201], v[104:107]
	v_mfma_f32_16x16x32_bf16 v[96:99], v[160:163], v[202:205], v[96:99]
	v_mfma_f32_16x16x32_bf16 v[92:95], v[164:167], v[190:193], v[92:95]
	v_mfma_f32_16x16x32_bf16 v[84:87], v[164:167], v[194:197], v[84:87]
	v_mfma_f32_16x16x32_bf16 v[88:91], v[164:167], v[198:201], v[88:91]
	v_mfma_f32_16x16x32_bf16 v[80:83], v[164:167], v[202:205], v[80:83]
	v_mfma_f32_16x16x32_bf16 v[76:79], v[168:171], v[190:193], v[76:79]
	v_mfma_f32_16x16x32_bf16 v[68:71], v[168:171], v[194:197], v[68:71]
	v_mfma_f32_16x16x32_bf16 v[72:75], v[168:171], v[198:201], v[72:75]
	v_mfma_f32_16x16x32_bf16 v[64:67], v[168:171], v[202:205], v[64:67]
	ds_read_b128 v[156:159], v155
	ds_read_b128 v[160:163], v155 offset:2048
	ds_read_b128 v[164:167], v155 offset:4096
	ds_read_b128 v[168:171], v155 offset:6144
	ds_read_b128 v[206:209], v222 offset:32768
	ds_read_b128 v[210:213], v222 offset:34816
	ds_read_b128 v[214:217], v222 offset:36864
	ds_read_b128 v[218:221], v222 offset:38912
	s_waitcnt lgkmcnt(8)
	v_mfma_f32_16x16x32_bf16 v[60:63], v[172:175], v[190:193], v[60:63]
	v_mfma_f32_16x16x32_bf16 v[52:55], v[172:175], v[194:197], v[52:55]
	v_mfma_f32_16x16x32_bf16 v[56:59], v[172:175], v[198:201], v[56:59]
	v_mfma_f32_16x16x32_bf16 v[48:51], v[172:175], v[202:205], v[48:51]
	v_mfma_f32_16x16x32_bf16 v[44:47], v[176:179], v[190:193], v[44:47]
	v_mfma_f32_16x16x32_bf16 v[36:39], v[176:179], v[194:197], v[36:39]
	v_mfma_f32_16x16x32_bf16 v[40:43], v[176:179], v[198:201], v[40:43]
	v_mfma_f32_16x16x32_bf16 v[32:35], v[176:179], v[202:205], v[32:35]
	v_mfma_f32_16x16x32_bf16 v[28:31], v[182:185], v[190:193], v[28:31]
	v_mfma_f32_16x16x32_bf16 v[16:19], v[182:185], v[194:197], v[16:19]
	v_mfma_f32_16x16x32_bf16 v[24:27], v[182:185], v[198:201], v[24:27]
	v_mfma_f32_16x16x32_bf16 v[12:15], v[182:185], v[202:205], v[12:15]
	v_mfma_f32_16x16x32_bf16 v[4:7], v[186:189], v[190:193], v[4:7]
	v_mfma_f32_16x16x32_bf16 v[0:3], v[186:189], v[194:197], v[0:3]
	v_mfma_f32_16x16x32_bf16 v[20:23], v[186:189], v[198:201], v[20:23]
	v_mfma_f32_16x16x32_bf16 v[8:11], v[186:189], v[202:205], v[8:11]
	ds_read_b128 v[172:175], v155 offset:8192
	ds_read_b128 v[176:179], v155 offset:10240
	ds_read_b128 v[182:185], v155 offset:12288
	ds_read_b128 v[186:189], v155 offset:14336
	s_waitcnt lgkmcnt(4)
	v_mfma_f32_16x16x32_bf16 v[124:127], v[156:159], v[206:209], v[124:127]
	v_mfma_f32_16x16x32_bf16 v[116:119], v[156:159], v[210:213], v[116:119]
	v_mfma_f32_16x16x32_bf16 v[120:123], v[156:159], v[214:217], v[120:123]
	v_mfma_f32_16x16x32_bf16 v[112:115], v[156:159], v[218:221], v[112:115]
	v_mfma_f32_16x16x32_bf16 v[108:111], v[160:163], v[206:209], v[108:111]
	v_mfma_f32_16x16x32_bf16 v[100:103], v[160:163], v[210:213], v[100:103]
	v_mfma_f32_16x16x32_bf16 v[104:107], v[160:163], v[214:217], v[104:107]
	v_mfma_f32_16x16x32_bf16 v[96:99], v[160:163], v[218:221], v[96:99]
	v_mfma_f32_16x16x32_bf16 v[92:95], v[164:167], v[206:209], v[92:95]
	v_mfma_f32_16x16x32_bf16 v[84:87], v[164:167], v[210:213], v[84:87]
	v_mfma_f32_16x16x32_bf16 v[88:91], v[164:167], v[214:217], v[88:91]
	v_mfma_f32_16x16x32_bf16 v[80:83], v[164:167], v[218:221], v[80:83]
	v_mfma_f32_16x16x32_bf16 v[76:79], v[168:171], v[206:209], v[76:79]
	v_mfma_f32_16x16x32_bf16 v[68:71], v[168:171], v[210:213], v[68:71]
	v_mfma_f32_16x16x32_bf16 v[72:75], v[168:171], v[214:217], v[72:75]
	v_mfma_f32_16x16x32_bf16 v[64:67], v[168:171], v[218:221], v[64:67]
	s_add_u32 s44, s44, 0x80
	s_addc_u32 s45, s45, 0
	s_add_i32 s43, s43, 1
	s_cmp_lt_u32 s43, 15
	s_cbranch_scc0 .Lg10_last
	s_waitcnt lgkmcnt(0)
	s_waitcnt vmcnt(0)
	s_barrier
	s_xor_b32 s57, s57, 0x10000
	s_mov_b32 m0, s57
	s_add_u32 s46, s44, s14
	s_addc_u32 s47, s45, s15
	global_load_lds_dwordx4 v144, s[46:47]
	s_add_u32 m0, s57, 0x2000
	s_add_u32 s46, s44, s16
	s_addc_u32 s47, s45, s17
	global_load_lds_dwordx4 v144, s[46:47]
	ds_read_b128 v[156:159], v223
	ds_read_b128 v[160:163], v223 offset:2048
	ds_read_b128 v[164:167], v223 offset:4096
	ds_read_b128 v[168:171], v223 offset:6144
	ds_read_b128 v[190:193], v225 offset:32768
	ds_read_b128 v[194:197], v225 offset:34816
	ds_read_b128 v[198:201], v225 offset:36864
	ds_read_b128 v[202:205], v225 offset:38912
	v_mfma_f32_16x16x32_bf16 v[60:63], v[172:175], v[206:209], v[60:63]
	v_mfma_f32_16x16x32_bf16 v[52:55], v[172:175], v[210:213], v[52:55]
	s_add_u32 m0, s57, 0x4000
	s_add_u32 s46, s44, s18
	s_addc_u32 s47, s45, s19
	global_load_lds_dwordx4 v144, s[46:47]
	v_mfma_f32_16x16x32_bf16 v[56:59], v[172:175], v[214:217], v[56:59]
	v_mfma_f32_16x16x32_bf16 v[48:51], v[172:175], v[218:221], v[48:51]
	s_add_u32 m0, s57, 0x6000
	s_add_u32 s46, s44, s22
	s_addc_u32 s47, s45, s23
	global_load_lds_dwordx4 v144, s[46:47]
	v_mfma_f32_16x16x32_bf16 v[44:47], v[176:179], v[206:209], v[44:47]
	v_mfma_f32_16x16x32_bf16 v[36:39], v[176:179], v[210:213], v[36:39]
	s_add_u32 m0, s57, 0x8000
	s_add_u32 s46, s44, s30
	s_addc_u32 s47, s45, s31
	global_load_lds_dwordx4 v145, s[46:47]
	v_mfma_f32_16x16x32_bf16 v[40:43], v[176:179], v[214:217], v[40:43]
	v_mfma_f32_16x16x32_bf16 v[32:35], v[176:179], v[218:221], v[32:35]
	s_add_u32 m0, s57, 0xa000
	s_add_u32 s46, s44, s36
	s_addc_u32 s47, s45, s37
	global_load_lds_dwordx4 v145, s[46:47]
	v_mfma_f32_16x16x32_bf16 v[28:31], v[182:185], v[206:209], v[28:31]
	v_mfma_f32_16x16x32_bf16 v[16:19], v[182:185], v[210:213], v[16:19]
	s_add_u32 m0, s57, 0xc000
	s_add_u32 s46, s44, s38
	s_addc_u32 s47, s45, s39
	global_load_lds_dwordx4 v145, s[46:47]
	v_mfma_f32_16x16x32_bf16 v[24:27], v[182:185], v[214:217], v[24:27]
	v_mfma_f32_16x16x32_bf16 v[12:15], v[182:185], v[218:221], v[12:15]
	s_add_u32 m0, s57, 0xe000
	s_add_u32 s46, s44, s40
	s_addc_u32 s47, s45, s41
	global_load_lds_dwordx4 v145, s[46:47]
	v_mfma_f32_16x16x32_bf16 v[4:7], v[186:189], v[206:209], v[4:7]
	v_mfma_f32_16x16x32_bf16 v[0:3], v[186:189], v[210:213], v[0:3]
	v_mfma_f32_16x16x32_bf16 v[20:23], v[186:189], v[214:217], v[20:23]
	v_mfma_f32_16x16x32_bf16 v[8:11], v[186:189], v[218:221], v[8:11]
	ds_read_b128 v[172:175], v223 offset:8192
	ds_read_b128 v[176:179], v223 offset:10240
	ds_read_b128 v[182:185], v223 offset:12288
	ds_read_b128 v[186:189], v223 offset:14336
	s_waitcnt lgkmcnt(4)
	v_mfma_f32_16x16x32_bf16 v[124:127], v[156:159], v[190:193], v[124:127]
	v_mfma_f32_16x16x32_bf16 v[116:119], v[156:159], v[194:197], v[116:119]
	v_mfma_f32_16x16x32_bf16 v[120:123], v[156:159], v[198:201], v[120:123]
	v_mfma_f32_16x16x32_bf16 v[112:115], v[156:159], v[202:205], v[112:115]
	v_mfma_f32_16x16x32_bf16 v[108:111], v[160:163], v[190:193], v[108:111]
	v_mfma_f32_16x16x32_bf16 v[100:103], v[160:163], v[194:197], v[100:103]
	v_mfma_f32_16x16x32_bf16 v[104:107], v[160:163], v[198:201], v[104:107]
	v_mfma_f32_16x16x32_bf16 v[96:99], v[160:163], v[202:205], v[96:99]
	v_mfma_f32_16x16x32_bf16 v[92:95], v[164:167], v[190:193], v[92:95]
	v_mfma_f32_16x16x32_bf16 v[84:87], v[164:167], v[194:197], v[84:87]
	v_mfma_f32_16x16x32_bf16 v[88:91], v[164:167], v[198:201], v[88:91]
	v_mfma_f32_16x16x32_bf16 v[80:83], v[164:167], v[202:205], v[80:83]
	v_mfma_f32_16x16x32_bf16 v[76:79], v[168:171], v[190:193], v[76:79]
	v_mfma_f32_16x16x32_bf16 v[68:71], v[168:171], v[194:197], v[68:71]
	v_mfma_f32_16x16x32_bf16 v[72:75], v[168:171], v[198:201], v[72:75]
	v_mfma_f32_16x16x32_bf16 v[64:67], v[168:171], v[202:205], v[64:67]
	ds_read_b128 v[156:159], v224
	ds_read_b128 v[160:163], v224 offset:2048
	ds_read_b128 v[164:167], v224 offset:4096
	ds_read_b128 v[168:171], v224 offset:6144
	ds_read_b128 v[206:209], v226 offset:32768
	ds_read_b128 v[210:213], v226 offset:34816
	ds_read_b128 v[214:217], v226 offset:36864
	ds_read_b128 v[218:221], v226 offset:38912
	s_waitcnt lgkmcnt(8)
	v_mfma_f32_16x16x32_bf16 v[60:63], v[172:175], v[190:193], v[60:63]
	v_mfma_f32_16x16x32_bf16 v[52:55], v[172:175], v[194:197], v[52:55]
	v_mfma_f32_16x16x32_bf16 v[56:59], v[172:175], v[198:201], v[56:59]
	v_mfma_f32_16x16x32_bf16 v[48:51], v[172:175], v[202:205], v[48:51]
	v_mfma_f32_16x16x32_bf16 v[44:47], v[176:179], v[190:193], v[44:47]
	v_mfma_f32_16x16x32_bf16 v[36:39], v[176:179], v[194:197], v[36:39]
	v_mfma_f32_16x16x32_bf16 v[40:43], v[176:179], v[198:201], v[40:43]
	v_mfma_f32_16x16x32_bf16 v[32:35], v[176:179], v[202:205], v[32:35]
	v_mfma_f32_16x16x32_bf16 v[28:31], v[182:185], v[190:193], v[28:31]
	v_mfma_f32_16x16x32_bf16 v[16:19], v[182:185], v[194:197], v[16:19]
	v_mfma_f32_16x16x32_bf16 v[24:27], v[182:185], v[198:201], v[24:27]
	v_mfma_f32_16x16x32_bf16 v[12:15], v[182:185], v[202:205], v[12:15]
	v_mfma_f32_16x16x32_bf16 v[4:7], v[186:189], v[190:193], v[4:7]
	v_mfma_f32_16x16x32_bf16 v[0:3], v[186:189], v[194:197], v[0:3]
	v_mfma_f32_16x16x32_bf16 v[20:23], v[186:189], v[198:201], v[20:23]
	v_mfma_f32_16x16x32_bf16 v[8:11], v[186:189], v[202:205], v[8:11]
	ds_read_b128 v[172:175], v224 offset:8192
	ds_read_b128 v[176:179], v224 offset:10240
	ds_read_b128 v[182:185], v224 offset:12288
	ds_read_b128 v[186:189], v224 offset:14336
	s_waitcnt lgkmcnt(4)
	v_mfma_f32_16x16x32_bf16 v[124:127], v[156:159], v[206:209], v[124:127]
	v_mfma_f32_16x16x32_bf16 v[116:119], v[156:159], v[210:213], v[116:119]
	v_mfma_f32_16x16x32_bf16 v[120:123], v[156:159], v[214:217], v[120:123]
	v_mfma_f32_16x16x32_bf16 v[112:115], v[156:159], v[218:221], v[112:115]
	v_mfma_f32_16x16x32_bf16 v[108:111], v[160:163], v[206:209], v[108:111]
	v_mfma_f32_16x16x32_bf16 v[100:103], v[160:163], v[210:213], v[100:103]
	v_mfma_f32_16x16x32_bf16 v[104:107], v[160:163], v[214:217], v[104:107]
	v_mfma_f32_16x16x32_bf16 v[96:99], v[160:163], v[218:221], v[96:99]
	v_mfma_f32_16x16x32_bf16 v[92:95], v[164:167], v[206:209], v[92:95]
	v_mfma_f32_16x16x32_bf16 v[84:87], v[164:167], v[210:213], v[84:87]
	v_mfma_f32_16x16x32_bf16 v[88:91], v[164:167], v[214:217], v[88:91]
	v_mfma_f32_16x16x32_bf16 v[80:83], v[164:167], v[218:221], v[80:83]
	v_mfma_f32_16x16x32_bf16 v[76:79], v[168:171], v[206:209], v[76:79]
	v_mfma_f32_16x16x32_bf16 v[68:71], v[168:171], v[210:213], v[68:71]
	v_mfma_f32_16x16x32_bf16 v[72:75], v[168:171], v[214:217], v[72:75]
	v_mfma_f32_16x16x32_bf16 v[64:67], v[168:171], v[218:221], v[64:67]
	s_add_u32 s44, s44, 0x80
	s_addc_u32 s45, s45, 0
	s_add_i32 s43, s43, 1
	s_branch .Lg10_top

.Lg11_top:
	s_waitcnt lgkmcnt(0)
	s_waitcnt vmcnt(0)
	s_barrier
	s_xor_b32 s45, s45, 0x10000
	s_mov_b32 m0, s45
	s_add_u32 s38, s36, s12
	s_addc_u32 s39, s37, s13
	global_load_lds_dwordx4 v178, s[38:39]
	s_add_u32 m0, s45, 0x2000
	s_add_u32 s38, s36, s14
	s_addc_u32 s39, s37, s15
	global_load_lds_dwordx4 v178, s[38:39]
	ds_read_b128 v[142:145], v141
	ds_read_b128 v[146:149], v141 offset:2048
	ds_read_b128 v[150:153], v141 offset:4096
	ds_read_b128 v[154:157], v141 offset:6144
	ds_read_b128 v[174:177], v210 offset:32768
	ds_read_b128 v[182:185], v210 offset:34816
	ds_read_b128 v[186:189], v210 offset:36864
	ds_read_b128 v[190:193], v210 offset:38912
	v_mfma_f32_16x16x32_bf16 v[60:63], v[158:161], v[194:197], v[60:63]
	v_mfma_f32_16x16x32_bf16 v[56:59], v[158:161], v[198:201], v[56:59]
	s_add_u32 m0, s45, 0x4000
	s_add_u32 s38, s36, s16
	s_addc_u32 s39, s37, s17
	global_load_lds_dwordx4 v178, s[38:39]
	v_mfma_f32_16x16x32_bf16 v[52:55], v[158:161], v[202:205], v[52:55]
	v_mfma_f32_16x16x32_bf16 v[48:51], v[158:161], v[206:209], v[48:51]
	s_add_u32 m0, s45, 0x6000
	s_add_u32 s38, s36, s18
	s_addc_u32 s39, s37, s19
	global_load_lds_dwordx4 v178, s[38:39]
	v_mfma_f32_16x16x32_bf16 v[44:47], v[162:165], v[194:197], v[44:47]
	v_mfma_f32_16x16x32_bf16 v[32:35], v[162:165], v[198:201], v[32:35]
	s_add_u32 m0, s45, 0x8000
	s_add_u32 s38, s36, s22
	s_addc_u32 s39, s37, s23
	global_load_lds_dwordx4 v179, s[38:39]
	v_mfma_f32_16x16x32_bf16 v[28:31], v[162:165], v[202:205], v[28:31]
	v_mfma_f32_16x16x32_bf16 v[24:27], v[162:165], v[206:209], v[24:27]
	s_add_u32 m0, s45, 0xa000
	s_add_u32 s38, s36, s24
	s_addc_u32 s39, s37, s25
	global_load_lds_dwordx4 v179, s[38:39]
	v_mfma_f32_16x16x32_bf16 v[20:23], v[166:169], v[194:197], v[20:23]
	v_mfma_f32_16x16x32_bf16 v[16:19], v[166:169], v[198:201], v[16:19]
	s_add_u32 m0, s45, 0xc000
	s_add_u32 s38, s36, s26
	s_addc_u32 s39, s37, s27
	global_load_lds_dwordx4 v179, s[38:39]
	v_mfma_f32_16x16x32_bf16 v[12:15], v[166:169], v[202:205], v[12:15]
	v_mfma_f32_16x16x32_bf16 v[8:11], v[166:169], v[206:209], v[8:11]
	s_add_u32 m0, s45, 0xe000
	s_add_u32 s38, s36, s28
	s_addc_u32 s39, s37, s29
	global_load_lds_dwordx4 v179, s[38:39]
	v_mfma_f32_16x16x32_bf16 v[4:7], v[170:173], v[194:197], v[4:7]
	v_mfma_f32_16x16x32_bf16 v[0:3], v[170:173], v[198:201], v[0:3]
	v_mfma_f32_16x16x32_bf16 v[40:43], v[170:173], v[202:205], v[40:43]
	v_mfma_f32_16x16x32_bf16 v[36:39], v[170:173], v[206:209], v[36:39]
.Lg11_entry:
	ds_read_b128 v[158:161], v141 offset:8192
	ds_read_b128 v[162:165], v141 offset:10240
	ds_read_b128 v[166:169], v141 offset:12288
	ds_read_b128 v[170:173], v141 offset:14336
	s_waitcnt lgkmcnt(4)
	v_mfma_f32_16x16x32_bf16 v[124:127], v[142:145], v[174:177], v[124:127]
	v_mfma_f32_16x16x32_bf16 v[120:123], v[142:145], v[182:185], v[120:123]
	v_mfma_f32_16x16x32_bf16 v[116:119], v[142:145], v[186:189], v[116:119]
	v_mfma_f32_16x16x32_bf16 v[112:115], v[142:145], v[190:193], v[112:115]
	v_mfma_f32_16x16x32_bf16 v[108:111], v[146:149], v[174:177], v[108:111]
	v_mfma_f32_16x16x32_bf16 v[104:107], v[146:149], v[182:185], v[104:107]
	v_mfma_f32_16x16x32_bf16 v[100:103], v[146:149], v[186:189], v[100:103]
	v_mfma_f32_16x16x32_bf16 v[96:99], v[146:149], v[190:193], v[96:99]
	v_mfma_f32_16x16x32_bf16 v[92:95], v[150:153], v[174:177], v[92:95]
	v_mfma_f32_16x16x32_bf16 v[88:91], v[150:153], v[182:185], v[88:91]
	v_mfma_f32_16x16x32_bf16 v[84:87], v[150:153], v[186:189], v[84:87]
	v_mfma_f32_16x16x32_bf16 v[80:83], v[150:153], v[190:193], v[80:83]
	v_mfma_f32_16x16x32_bf16 v[76:79], v[154:157], v[174:177], v[76:79]
	v_mfma_f32_16x16x32_bf16 v[72:75], v[154:157], v[182:185], v[72:75]
	v_mfma_f32_16x16x32_bf16 v[68:71], v[154:157], v[186:189], v[68:71]
	v_mfma_f32_16x16x32_bf16 v[64:67], v[154:157], v[190:193], v[64:67]
	ds_read_b128 v[142:145], v180
	ds_read_b128 v[146:149], v180 offset:2048
	ds_read_b128 v[150:153], v180 offset:4096
	ds_read_b128 v[154:157], v180 offset:6144
	ds_read_b128 v[194:197], v211 offset:32768
	ds_read_b128 v[198:201], v211 offset:34816
	ds_read_b128 v[202:205], v211 offset:36864
	ds_read_b128 v[206:209], v211 offset:38912
	s_waitcnt lgkmcnt(8)
	v_mfma_f32_16x16x32_bf16 v[60:63], v[158:161], v[174:177], v[60:63]
	v_mfma_f32_16x16x32_bf16 v[56:59], v[158:161], v[182:185], v[56:59]
	v_mfma_f32_16x16x32_bf16 v[52:55], v[158:161], v[186:189], v[52:55]
	v_mfma_f32_16x16x32_bf16 v[48:51], v[158:161], v[190:193], v[48:51]
	v_mfma_f32_16x16x32_bf16 v[44:47], v[162:165], v[174:177], v[44:47]
	v_mfma_f32_16x16x32_bf16 v[32:35], v[162:165], v[182:185], v[32:35]
	v_mfma_f32_16x16x32_bf16 v[28:31], v[162:165], v[186:189], v[28:31]
	v_mfma_f32_16x16x32_bf16 v[24:27], v[162:165], v[190:193], v[24:27]
	v_mfma_f32_16x16x32_bf16 v[20:23], v[166:169], v[174:177], v[20:23]
	v_mfma_f32_16x16x32_bf16 v[16:19], v[166:169], v[182:185], v[16:19]
	v_mfma_f32_16x16x32_bf16 v[12:15], v[166:169], v[186:189], v[12:15]
	v_mfma_f32_16x16x32_bf16 v[8:11], v[166:169], v[190:193], v[8:11]
	v_mfma_f32_16x16x32_bf16 v[4:7], v[170:173], v[174:177], v[4:7]
	v_mfma_f32_16x16x32_bf16 v[0:3], v[170:173], v[182:185], v[0:3]
	v_mfma_f32_16x16x32_bf16 v[40:43], v[170:173], v[186:189], v[40:43]
	v_mfma_f32_16x16x32_bf16 v[36:39], v[170:173], v[190:193], v[36:39]
	ds_read_b128 v[158:161], v180 offset:8192
	ds_read_b128 v[162:165], v180 offset:10240
	ds_read_b128 v[166:169], v180 offset:12288
	ds_read_b128 v[170:173], v180 offset:14336
	s_waitcnt lgkmcnt(4)
	v_mfma_f32_16x16x32_bf16 v[124:127], v[142:145], v[194:197], v[124:127]
	v_mfma_f32_16x16x32_bf16 v[120:123], v[142:145], v[198:201], v[120:123]
	v_mfma_f32_16x16x32_bf16 v[116:119], v[142:145], v[202:205], v[116:119]
	v_mfma_f32_16x16x32_bf16 v[112:115], v[142:145], v[206:209], v[112:115]
	v_mfma_f32_16x16x32_bf16 v[108:111], v[146:149], v[194:197], v[108:111]
	v_mfma_f32_16x16x32_bf16 v[104:107], v[146:149], v[198:201], v[104:107]
	v_mfma_f32_16x16x32_bf16 v[100:103], v[146:149], v[202:205], v[100:103]
	v_mfma_f32_16x16x32_bf16 v[96:99], v[146:149], v[206:209], v[96:99]
	v_mfma_f32_16x16x32_bf16 v[92:95], v[150:153], v[194:197], v[92:95]
	v_mfma_f32_16x16x32_bf16 v[88:91], v[150:153], v[198:201], v[88:91]
	v_mfma_f32_16x16x32_bf16 v[84:87], v[150:153], v[202:205], v[84:87]
	v_mfma_f32_16x16x32_bf16 v[80:83], v[150:153], v[206:209], v[80:83]
	v_mfma_f32_16x16x32_bf16 v[76:79], v[154:157], v[194:197], v[76:79]
	v_mfma_f32_16x16x32_bf16 v[72:75], v[154:157], v[198:201], v[72:75]
	v_mfma_f32_16x16x32_bf16 v[68:71], v[154:157], v[202:205], v[68:71]
	v_mfma_f32_16x16x32_bf16 v[64:67], v[154:157], v[206:209], v[64:67]
	s_add_u32 s36, s36, 0x80
	s_addc_u32 s37, s37, 0
	s_add_i32 s31, s31, 1
	s_cmp_lt_u32 s31, 31
	s_cbranch_scc0 .Lg11_last
	s_waitcnt lgkmcnt(0)
	s_waitcnt vmcnt(0)
	s_barrier
	s_xor_b32 s45, s45, 0x10000
	s_mov_b32 m0, s45
	s_add_u32 s38, s36, s12
	s_addc_u32 s39, s37, s13
	global_load_lds_dwordx4 v178, s[38:39]
	s_add_u32 m0, s45, 0x2000
	s_add_u32 s38, s36, s14
	s_addc_u32 s39, s37, s15
	global_load_lds_dwordx4 v178, s[38:39]
	ds_read_b128 v[142:145], v212
	ds_read_b128 v[146:149], v212 offset:2048
	ds_read_b128 v[150:153], v212 offset:4096
	ds_read_b128 v[154:157], v212 offset:6144
	ds_read_b128 v[174:177], v214 offset:32768
	ds_read_b128 v[182:185], v214 offset:34816
	ds_read_b128 v[186:189], v214 offset:36864
	ds_read_b128 v[190:193], v214 offset:38912
	v_mfma_f32_16x16x32_bf16 v[60:63], v[158:161], v[194:197], v[60:63]
	v_mfma_f32_16x16x32_bf16 v[56:59], v[158:161], v[198:201], v[56:59]
	s_add_u32 m0, s45, 0x4000
	s_add_u32 s38, s36, s16
	s_addc_u32 s39, s37, s17
	global_load_lds_dwordx4 v178, s[38:39]
	v_mfma_f32_16x16x32_bf16 v[52:55], v[158:161], v[202:205], v[52:55]
	v_mfma_f32_16x16x32_bf16 v[48:51], v[158:161], v[206:209], v[48:51]
	s_add_u32 m0, s45, 0x6000
	s_add_u32 s38, s36, s18
	s_addc_u32 s39, s37, s19
	global_load_lds_dwordx4 v178, s[38:39]
	v_mfma_f32_16x16x32_bf16 v[44:47], v[162:165], v[194:197], v[44:47]
	v_mfma_f32_16x16x32_bf16 v[32:35], v[162:165], v[198:201], v[32:35]
	s_add_u32 m0, s45, 0x8000
	s_add_u32 s38, s36, s22
	s_addc_u32 s39, s37, s23
	global_load_lds_dwordx4 v179, s[38:39]
	v_mfma_f32_16x16x32_bf16 v[28:31], v[162:165], v[202:205], v[28:31]
	v_mfma_f32_16x16x32_bf16 v[24:27], v[162:165], v[206:209], v[24:27]
	s_add_u32 m0, s45, 0xa000
	s_add_u32 s38, s36, s24
	s_addc_u32 s39, s37, s25
	global_load_lds_dwordx4 v179, s[38:39]
	v_mfma_f32_16x16x32_bf16 v[20:23], v[166:169], v[194:197], v[20:23]
	v_mfma_f32_16x16x32_bf16 v[16:19], v[166:169], v[198:201], v[16:19]
	s_add_u32 m0, s45, 0xc000
	s_add_u32 s38, s36, s26
	s_addc_u32 s39, s37, s27
	global_load_lds_dwordx4 v179, s[38:39]
	v_mfma_f32_16x16x32_bf16 v[12:15], v[166:169], v[202:205], v[12:15]
	v_mfma_f32_16x16x32_bf16 v[8:11], v[166:169], v[206:209], v[8:11]
	s_add_u32 m0, s45, 0xe000
	s_add_u32 s38, s36, s28
	s_addc_u32 s39, s37, s29
	global_load_lds_dwordx4 v179, s[38:39]
	v_mfma_f32_16x16x32_bf16 v[4:7], v[170:173], v[194:197], v[4:7]
	v_mfma_f32_16x16x32_bf16 v[0:3], v[170:173], v[198:201], v[0:3]
	v_mfma_f32_16x16x32_bf16 v[40:43], v[170:173], v[202:205], v[40:43]
	v_mfma_f32_16x16x32_bf16 v[36:39], v[170:173], v[206:209], v[36:39]
	ds_read_b128 v[158:161], v212 offset:8192
	ds_read_b128 v[162:165], v212 offset:10240
	ds_read_b128 v[166:169], v212 offset:12288
	ds_read_b128 v[170:173], v212 offset:14336
	s_waitcnt lgkmcnt(4)
	v_mfma_f32_16x16x32_bf16 v[124:127], v[142:145], v[174:177], v[124:127]
	v_mfma_f32_16x16x32_bf16 v[120:123], v[142:145], v[182:185], v[120:123]
	v_mfma_f32_16x16x32_bf16 v[116:119], v[142:145], v[186:189], v[116:119]
	v_mfma_f32_16x16x32_bf16 v[112:115], v[142:145], v[190:193], v[112:115]
	v_mfma_f32_16x16x32_bf16 v[108:111], v[146:149], v[174:177], v[108:111]
	v_mfma_f32_16x16x32_bf16 v[104:107], v[146:149], v[182:185], v[104:107]
	v_mfma_f32_16x16x32_bf16 v[100:103], v[146:149], v[186:189], v[100:103]
	v_mfma_f32_16x16x32_bf16 v[96:99], v[146:149], v[190:193], v[96:99]
	v_mfma_f32_16x16x32_bf16 v[92:95], v[150:153], v[174:177], v[92:95]
	v_mfma_f32_16x16x32_bf16 v[88:91], v[150:153], v[182:185], v[88:91]
	v_mfma_f32_16x16x32_bf16 v[84:87], v[150:153], v[186:189], v[84:87]
	v_mfma_f32_16x16x32_bf16 v[80:83], v[150:153], v[190:193], v[80:83]
	v_mfma_f32_16x16x32_bf16 v[76:79], v[154:157], v[174:177], v[76:79]
	v_mfma_f32_16x16x32_bf16 v[72:75], v[154:157], v[182:185], v[72:75]
	v_mfma_f32_16x16x32_bf16 v[68:71], v[154:157], v[186:189], v[68:71]
	v_mfma_f32_16x16x32_bf16 v[64:67], v[154:157], v[190:193], v[64:67]
	ds_read_b128 v[142:145], v213
	ds_read_b128 v[146:149], v213 offset:2048
	ds_read_b128 v[150:153], v213 offset:4096
	ds_read_b128 v[154:157], v213 offset:6144
	ds_read_b128 v[194:197], v215 offset:32768
	ds_read_b128 v[198:201], v215 offset:34816
	ds_read_b128 v[202:205], v215 offset:36864
	ds_read_b128 v[206:209], v215 offset:38912
	s_waitcnt lgkmcnt(8)
	v_mfma_f32_16x16x32_bf16 v[60:63], v[158:161], v[174:177], v[60:63]
	v_mfma_f32_16x16x32_bf16 v[56:59], v[158:161], v[182:185], v[56:59]
	v_mfma_f32_16x16x32_bf16 v[52:55], v[158:161], v[186:189], v[52:55]
	v_mfma_f32_16x16x32_bf16 v[48:51], v[158:161], v[190:193], v[48:51]
	v_mfma_f32_16x16x32_bf16 v[44:47], v[162:165], v[174:177], v[44:47]
	v_mfma_f32_16x16x32_bf16 v[32:35], v[162:165], v[182:185], v[32:35]
	v_mfma_f32_16x16x32_bf16 v[28:31], v[162:165], v[186:189], v[28:31]
	v_mfma_f32_16x16x32_bf16 v[24:27], v[162:165], v[190:193], v[24:27]
	v_mfma_f32_16x16x32_bf16 v[20:23], v[166:169], v[174:177], v[20:23]
	v_mfma_f32_16x16x32_bf16 v[16:19], v[166:169], v[182:185], v[16:19]
	v_mfma_f32_16x16x32_bf16 v[12:15], v[166:169], v[186:189], v[12:15]
	v_mfma_f32_16x16x32_bf16 v[8:11], v[166:169], v[190:193], v[8:11]
	v_mfma_f32_16x16x32_bf16 v[4:7], v[170:173], v[174:177], v[4:7]
	v_mfma_f32_16x16x32_bf16 v[0:3], v[170:173], v[182:185], v[0:3]
	v_mfma_f32_16x16x32_bf16 v[40:43], v[170:173], v[186:189], v[40:43]
	v_mfma_f32_16x16x32_bf16 v[36:39], v[170:173], v[190:193], v[36:39]
	ds_read_b128 v[158:161], v213 offset:8192
	ds_read_b128 v[162:165], v213 offset:10240
	ds_read_b128 v[166:169], v213 offset:12288
	ds_read_b128 v[170:173], v213 offset:14336
	s_waitcnt lgkmcnt(4)
	v_mfma_f32_16x16x32_bf16 v[124:127], v[142:145], v[194:197], v[124:127]
	v_mfma_f32_16x16x32_bf16 v[120:123], v[142:145], v[198:201], v[120:123]
	v_mfma_f32_16x16x32_bf16 v[116:119], v[142:145], v[202:205], v[116:119]
	v_mfma_f32_16x16x32_bf16 v[112:115], v[142:145], v[206:209], v[112:115]
	v_mfma_f32_16x16x32_bf16 v[108:111], v[146:149], v[194:197], v[108:111]
	v_mfma_f32_16x16x32_bf16 v[104:107], v[146:149], v[198:201], v[104:107]
	v_mfma_f32_16x16x32_bf16 v[100:103], v[146:149], v[202:205], v[100:103]
	v_mfma_f32_16x16x32_bf16 v[96:99], v[146:149], v[206:209], v[96:99]
	v_mfma_f32_16x16x32_bf16 v[92:95], v[150:153], v[194:197], v[92:95]
	v_mfma_f32_16x16x32_bf16 v[88:91], v[150:153], v[198:201], v[88:91]
	v_mfma_f32_16x16x32_bf16 v[84:87], v[150:153], v[202:205], v[84:87]
	v_mfma_f32_16x16x32_bf16 v[80:83], v[150:153], v[206:209], v[80:83]
	v_mfma_f32_16x16x32_bf16 v[76:79], v[154:157], v[194:197], v[76:79]
	v_mfma_f32_16x16x32_bf16 v[72:75], v[154:157], v[198:201], v[72:75]
	v_mfma_f32_16x16x32_bf16 v[68:71], v[154:157], v[202:205], v[68:71]
	v_mfma_f32_16x16x32_bf16 v[64:67], v[154:157], v[206:209], v[64:67]
	s_add_u32 s36, s36, 0x80
	s_addc_u32 s37, s37, 0
	s_add_i32 s31, s31, 1
	s_branch .Lg11_top
